# phase 1 (RMSNorm rows + bias2 GEMV) rewritten by hand as per-wave streams with a 4-row load ring
# baseline (speedup 1.0000x reference)
.LBB0_135:
	s_cmp_lt_i32 s76, 2
	s_cselect_b64 s[0:1], -1, 0
	s_and_b64 s[4:5], s[0:1], s[2:3]
	s_andn2_b64 vcc, exec, s[4:5]
	s_cbranch_vccnz .LBB0_145
	v_and_b32_e32 v2, 63, v188
	v_lshlrev_b32_e32 v0, 4, v2
	v_lshlrev_b32_e32 v1, 3, v2
	v_readfirstlane_b32 s7, v188
	v_mov_b32_e32 v16, 0x3a800000
	v_mov_b32_e32 v17, 0x358637bd
	v_mov_b32_e32 v18, 1.0
	v_mov_b32_e32 v19, 1.0
	s_lshr_b32 s7, s7, 6
	s_lshl_b32 s6, s33, 3
	s_add_i32 s6, s6, s7
	s_add_u32 s12, s74, 0x5000
	s_addc_u32 s13, s75, 0
	s_cmpk_lt_u32 s6, 0x400
	s_cbranch_scc0 .Lp1_noctx0
	s_lshl_b32 s14, s6, 12
	s_add_u32 s14, s44, s14
	s_addc_u32 s15, s45, 0
	global_load_dwordx4 v[132:135], v0, s[14:15]
	global_load_dwordx4 v[136:139], v0, s[14:15] offset:1024
	global_load_dwordx4 v[140:143], v0, s[14:15] offset:2048
	global_load_dwordx4 v[144:147], v0, s[14:15] offset:3072
.Lp1_noctx0:
	global_load_dwordx4 v[20:23], v0, s[52:53]
	global_load_dwordx4 v[24:27], v0, s[52:53] offset:1024
	global_load_dwordx4 v[28:31], v0, s[52:53] offset:2048
	global_load_dwordx4 v[32:35], v0, s[52:53] offset:3072
	s_add_u32 s14, s12, 0x0
	s_addc_u32 s15, s13, 0
	s_add_u32 s16, s14, 0x1000
	s_addc_u32 s17, s15, 0
	global_load_dwordx4 v[36:39], v0, s[14:15]
	global_load_dwordx4 v[40:43], v0, s[14:15] offset:1024
	global_load_dwordx4 v[44:47], v0, s[14:15] offset:2048
	global_load_dwordx4 v[48:51], v0, s[14:15] offset:3072
	global_load_dwordx4 v[52:55], v0, s[16:17]
	global_load_dwordx4 v[56:59], v0, s[16:17] offset:1024
	global_load_dwordx4 v[60:63], v0, s[16:17] offset:2048
	global_load_dwordx4 v[64:67], v0, s[16:17] offset:3072
	s_lshl_b32 s16, s7, 8
	s_add_i32 s16, s16, s33
	s_cmpk_lt_u32 s16, 0x580
	s_cbranch_scc0 .Lp1_nob0
	s_mul_i32 s17, s16, 0xba3
	s_lshr_b32 s17, s17, 16
	s_mul_i32 s18, s17, 22
	s_sub_i32 s18, s16, s18
	s_mul_i32 s19, s17, 0x58000
	s_add_u32 s22, s84, s19
	s_addc_u32 s23, s85, 0
	v_and_b32_e32 v3, 31, v2
	v_lshrrev_b32_e32 v8, 5, v2
	v_lshlrev_b32_e32 v3, 4, v3
	s_lshl_b32 s19, s18, 9
	v_mul_u32_u24_e32 v8, 0x2c00, v8
	v_add_u32_e32 v190, v8, v3
	v_add_u32_e32 v190, s19, v190
	global_load_dwordx4 v[148:151], v190, s[22:23]
	s_add_u32 s22, s22, 0x5800
	s_addc_u32 s23, s23, 0
	global_load_dwordx4 v[152:155], v190, s[22:23]
	s_add_u32 s22, s22, 0x5800
	s_addc_u32 s23, s23, 0
	global_load_dwordx4 v[156:159], v190, s[22:23]
	s_add_u32 s22, s22, 0x5800
	s_addc_u32 s23, s23, 0
	global_load_dwordx4 v[160:163], v190, s[22:23]
	s_add_u32 s22, s22, 0x5800
	s_addc_u32 s23, s23, 0
	global_load_dwordx4 v[164:167], v190, s[22:23]
	s_add_u32 s22, s22, 0x5800
	s_addc_u32 s23, s23, 0
	global_load_dwordx4 v[168:171], v190, s[22:23]
	s_add_u32 s22, s22, 0x5800
	s_addc_u32 s23, s23, 0
	global_load_dwordx4 v[172:175], v190, s[22:23]
	s_add_u32 s22, s22, 0x5800
	s_addc_u32 s23, s23, 0
	global_load_dwordx4 v[176:179], v190, s[22:23]
	s_add_u32 s22, s22, 0x5800
	s_addc_u32 s23, s23, 0
	global_load_dwordx4 v[180:183], v190, s[22:23]
	s_add_u32 s22, s22, 0x5800
	s_addc_u32 s23, s23, 0
	global_load_dwordx4 v[184:187], v190, s[22:23]
	s_add_u32 s22, s22, 0x5800
	s_addc_u32 s23, s23, 0
	global_load_dwordx4 v[192:195], v190, s[22:23]
	s_add_u32 s22, s22, 0x5800
	s_addc_u32 s23, s23, 0
	global_load_dwordx4 v[196:199], v190, s[22:23]
	s_add_u32 s22, s22, 0x5800
	s_addc_u32 s23, s23, 0
	global_load_dwordx4 v[200:203], v190, s[22:23]
	s_add_u32 s22, s22, 0x5800
	s_addc_u32 s23, s23, 0
	global_load_dwordx4 v[204:207], v190, s[22:23]
	s_add_u32 s22, s22, 0x5800
	s_addc_u32 s23, s23, 0
	global_load_dwordx4 v[208:211], v190, s[22:23]
	s_add_u32 s22, s22, 0x5800
	s_addc_u32 s23, s23, 0
	global_load_dwordx4 v[212:215], v190, s[22:23]
	v_lshrrev_b32_e32 v8, 4, v2
	v_and_b32_e32 v3, 15, v2
	v_lshlrev_b32_e32 v3, 2, v3
	v_mul_u32_u24_e32 v8, 0x6000, v8
	v_add_u32_e32 v191, v8, v3
	s_lshl_b32 s19, s17, 6
	s_addk_i32 s19, 0x3000
	v_add_u32_e32 v191, s19, v191
	global_load_dword v189, v191, s[12:13]
.Lp1_nob0:
	s_lshl_b32 s8, s6, 12
	s_add_u32 s8, s40, s8
	s_addc_u32 s9, s41, 0
	global_load_dwordx4 v[68:71], v0, s[8:9]
	global_load_dwordx4 v[72:75], v0, s[8:9] offset:1024
	global_load_dwordx4 v[76:79], v0, s[8:9] offset:2048
	global_load_dwordx4 v[80:83], v0, s[8:9] offset:3072
	s_add_u32 s8, s8, 0x800000
	s_addc_u32 s9, s9, 0
	global_load_dwordx4 v[84:87], v0, s[8:9]
	global_load_dwordx4 v[88:91], v0, s[8:9] offset:1024
	global_load_dwordx4 v[92:95], v0, s[8:9] offset:2048
	global_load_dwordx4 v[96:99], v0, s[8:9] offset:3072
	s_add_u32 s8, s8, 0x800000
	s_addc_u32 s9, s9, 0
	global_load_dwordx4 v[100:103], v0, s[8:9]
	global_load_dwordx4 v[104:107], v0, s[8:9] offset:1024
	global_load_dwordx4 v[108:111], v0, s[8:9] offset:2048
	global_load_dwordx4 v[112:115], v0, s[8:9] offset:3072
	s_add_u32 s8, s8, 0x800000
	s_addc_u32 s9, s9, 0
	global_load_dwordx4 v[116:119], v0, s[8:9]
	global_load_dwordx4 v[120:123], v0, s[8:9] offset:1024
	global_load_dwordx4 v[124:127], v0, s[8:9] offset:2048
	global_load_dwordx4 v[128:131], v0, s[8:9] offset:3072
	s_add_u32 s8, s8, 0x800000
	s_addc_u32 s9, s9, 0
	s_lshl_b32 s10, s6, 11
	s_add_u32 s10, s10, 0x1e85000
	s_addc_u32 s11, 0, 0
	s_add_u32 s10, s74, s10
	s_addc_u32 s11, s75, s11
	s_cmpk_lt_u32 s16, 0x580
	s_cbranch_scc0 .Lp1_nob1
	s_waitcnt vmcnt(16)
	v_readlane_b32 s24, v189, 0
	v_readlane_b32 s25, v189, 16
	v_readlane_b32 s26, v189, 32
	v_readlane_b32 s27, v189, 48
	v_mul_f32_e32 v216, s24, v148
	v_mul_f32_e32 v217, s24, v149
	v_mul_f32_e32 v218, s24, v150
	v_mul_f32_e32 v219, s24, v151
	v_mul_f32_e32 v220, s25, v148
	v_mul_f32_e32 v221, s25, v149
	v_mul_f32_e32 v222, s25, v150
	v_mul_f32_e32 v223, s25, v151
	v_mul_f32_e32 v224, s26, v148
	v_mul_f32_e32 v225, s26, v149
	v_mul_f32_e32 v226, s26, v150
	v_mul_f32_e32 v227, s26, v151
	v_mul_f32_e32 v228, s27, v148
	v_mul_f32_e32 v229, s27, v149
	v_mul_f32_e32 v230, s27, v150
	v_mul_f32_e32 v231, s27, v151
	v_readlane_b32 s24, v189, 1
	v_readlane_b32 s25, v189, 17
	v_readlane_b32 s26, v189, 33
	v_readlane_b32 s27, v189, 49
	v_fmac_f32_e32 v216, s24, v152
	v_fmac_f32_e32 v217, s24, v153
	v_fmac_f32_e32 v218, s24, v154
	v_fmac_f32_e32 v219, s24, v155
	v_fmac_f32_e32 v220, s25, v152
	v_fmac_f32_e32 v221, s25, v153
	v_fmac_f32_e32 v222, s25, v154
	v_fmac_f32_e32 v223, s25, v155
	v_fmac_f32_e32 v224, s26, v152
	v_fmac_f32_e32 v225, s26, v153
	v_fmac_f32_e32 v226, s26, v154
	v_fmac_f32_e32 v227, s26, v155
	v_fmac_f32_e32 v228, s27, v152
	v_fmac_f32_e32 v229, s27, v153
	v_fmac_f32_e32 v230, s27, v154
	v_fmac_f32_e32 v231, s27, v155
	v_readlane_b32 s24, v189, 2
	v_readlane_b32 s25, v189, 18
	v_readlane_b32 s26, v189, 34
	v_readlane_b32 s27, v189, 50
	v_fmac_f32_e32 v216, s24, v156
	v_fmac_f32_e32 v217, s24, v157
	v_fmac_f32_e32 v218, s24, v158
	v_fmac_f32_e32 v219, s24, v159
	v_fmac_f32_e32 v220, s25, v156
	v_fmac_f32_e32 v221, s25, v157
	v_fmac_f32_e32 v222, s25, v158
	v_fmac_f32_e32 v223, s25, v159
	v_fmac_f32_e32 v224, s26, v156
	v_fmac_f32_e32 v225, s26, v157
	v_fmac_f32_e32 v226, s26, v158
	v_fmac_f32_e32 v227, s26, v159
	v_fmac_f32_e32 v228, s27, v156
	v_fmac_f32_e32 v229, s27, v157
	v_fmac_f32_e32 v230, s27, v158
	v_fmac_f32_e32 v231, s27, v159
	v_readlane_b32 s24, v189, 3
	v_readlane_b32 s25, v189, 19
	v_readlane_b32 s26, v189, 35
	v_readlane_b32 s27, v189, 51
	v_fmac_f32_e32 v216, s24, v160
	v_fmac_f32_e32 v217, s24, v161
	v_fmac_f32_e32 v218, s24, v162
	v_fmac_f32_e32 v219, s24, v163
	v_fmac_f32_e32 v220, s25, v160
	v_fmac_f32_e32 v221, s25, v161
	v_fmac_f32_e32 v222, s25, v162
	v_fmac_f32_e32 v223, s25, v163
	v_fmac_f32_e32 v224, s26, v160
	v_fmac_f32_e32 v225, s26, v161
	v_fmac_f32_e32 v226, s26, v162
	v_fmac_f32_e32 v227, s26, v163
	v_fmac_f32_e32 v228, s27, v160
	v_fmac_f32_e32 v229, s27, v161
	v_fmac_f32_e32 v230, s27, v162
	v_fmac_f32_e32 v231, s27, v163
	v_readlane_b32 s24, v189, 4
	v_readlane_b32 s25, v189, 20
	v_readlane_b32 s26, v189, 36
	v_readlane_b32 s27, v189, 52
	v_fmac_f32_e32 v216, s24, v164
	v_fmac_f32_e32 v217, s24, v165
	v_fmac_f32_e32 v218, s24, v166
	v_fmac_f32_e32 v219, s24, v167
	v_fmac_f32_e32 v220, s25, v164
	v_fmac_f32_e32 v221, s25, v165
	v_fmac_f32_e32 v222, s25, v166
	v_fmac_f32_e32 v223, s25, v167
	v_fmac_f32_e32 v224, s26, v164
	v_fmac_f32_e32 v225, s26, v165
	v_fmac_f32_e32 v226, s26, v166
	v_fmac_f32_e32 v227, s26, v167
	v_fmac_f32_e32 v228, s27, v164
	v_fmac_f32_e32 v229, s27, v165
	v_fmac_f32_e32 v230, s27, v166
	v_fmac_f32_e32 v231, s27, v167
	v_readlane_b32 s24, v189, 5
	v_readlane_b32 s25, v189, 21
	v_readlane_b32 s26, v189, 37
	v_readlane_b32 s27, v189, 53
	v_fmac_f32_e32 v216, s24, v168
	v_fmac_f32_e32 v217, s24, v169
	v_fmac_f32_e32 v218, s24, v170
	v_fmac_f32_e32 v219, s24, v171
	v_fmac_f32_e32 v220, s25, v168
	v_fmac_f32_e32 v221, s25, v169
	v_fmac_f32_e32 v222, s25, v170
	v_fmac_f32_e32 v223, s25, v171
	v_fmac_f32_e32 v224, s26, v168
	v_fmac_f32_e32 v225, s26, v169
	v_fmac_f32_e32 v226, s26, v170
	v_fmac_f32_e32 v227, s26, v171
	v_fmac_f32_e32 v228, s27, v168
	v_fmac_f32_e32 v229, s27, v169
	v_fmac_f32_e32 v230, s27, v170
	v_fmac_f32_e32 v231, s27, v171
	v_readlane_b32 s24, v189, 6
	v_readlane_b32 s25, v189, 22
	v_readlane_b32 s26, v189, 38
	v_readlane_b32 s27, v189, 54
	v_fmac_f32_e32 v216, s24, v172
	v_fmac_f32_e32 v217, s24, v173
	v_fmac_f32_e32 v218, s24, v174
	v_fmac_f32_e32 v219, s24, v175
	v_fmac_f32_e32 v220, s25, v172
	v_fmac_f32_e32 v221, s25, v173
	v_fmac_f32_e32 v222, s25, v174
	v_fmac_f32_e32 v223, s25, v175
	v_fmac_f32_e32 v224, s26, v172
	v_fmac_f32_e32 v225, s26, v173
	v_fmac_f32_e32 v226, s26, v174
	v_fmac_f32_e32 v227, s26, v175
	v_fmac_f32_e32 v228, s27, v172
	v_fmac_f32_e32 v229, s27, v173
	v_fmac_f32_e32 v230, s27, v174
	v_fmac_f32_e32 v231, s27, v175
	v_readlane_b32 s24, v189, 7
	v_readlane_b32 s25, v189, 23
	v_readlane_b32 s26, v189, 39
	v_readlane_b32 s27, v189, 55
	v_fmac_f32_e32 v216, s24, v176
	v_fmac_f32_e32 v217, s24, v177
	v_fmac_f32_e32 v218, s24, v178
	v_fmac_f32_e32 v219, s24, v179
	v_fmac_f32_e32 v220, s25, v176
	v_fmac_f32_e32 v221, s25, v177
	v_fmac_f32_e32 v222, s25, v178
	v_fmac_f32_e32 v223, s25, v179
	v_fmac_f32_e32 v224, s26, v176
	v_fmac_f32_e32 v225, s26, v177
	v_fmac_f32_e32 v226, s26, v178
	v_fmac_f32_e32 v227, s26, v179
	v_fmac_f32_e32 v228, s27, v176
	v_fmac_f32_e32 v229, s27, v177
	v_fmac_f32_e32 v230, s27, v178
	v_fmac_f32_e32 v231, s27, v179
	v_readlane_b32 s24, v189, 8
	v_readlane_b32 s25, v189, 24
	v_readlane_b32 s26, v189, 40
	v_readlane_b32 s27, v189, 56
	v_fmac_f32_e32 v216, s24, v180
	v_fmac_f32_e32 v217, s24, v181
	v_fmac_f32_e32 v218, s24, v182
	v_fmac_f32_e32 v219, s24, v183
	v_fmac_f32_e32 v220, s25, v180
	v_fmac_f32_e32 v221, s25, v181
	v_fmac_f32_e32 v222, s25, v182
	v_fmac_f32_e32 v223, s25, v183
	v_fmac_f32_e32 v224, s26, v180
	v_fmac_f32_e32 v225, s26, v181
	v_fmac_f32_e32 v226, s26, v182
	v_fmac_f32_e32 v227, s26, v183
	v_fmac_f32_e32 v228, s27, v180
	v_fmac_f32_e32 v229, s27, v181
	v_fmac_f32_e32 v230, s27, v182
	v_fmac_f32_e32 v231, s27, v183
	v_readlane_b32 s24, v189, 9
	v_readlane_b32 s25, v189, 25
	v_readlane_b32 s26, v189, 41
	v_readlane_b32 s27, v189, 57
	v_fmac_f32_e32 v216, s24, v184
	v_fmac_f32_e32 v217, s24, v185
	v_fmac_f32_e32 v218, s24, v186
	v_fmac_f32_e32 v219, s24, v187
	v_fmac_f32_e32 v220, s25, v184
	v_fmac_f32_e32 v221, s25, v185
	v_fmac_f32_e32 v222, s25, v186
	v_fmac_f32_e32 v223, s25, v187
	v_fmac_f32_e32 v224, s26, v184
	v_fmac_f32_e32 v225, s26, v185
	v_fmac_f32_e32 v226, s26, v186
	v_fmac_f32_e32 v227, s26, v187
	v_fmac_f32_e32 v228, s27, v184
	v_fmac_f32_e32 v229, s27, v185
	v_fmac_f32_e32 v230, s27, v186
	v_fmac_f32_e32 v231, s27, v187
	v_readlane_b32 s24, v189, 10
	v_readlane_b32 s25, v189, 26
	v_readlane_b32 s26, v189, 42
	v_readlane_b32 s27, v189, 58
	v_fmac_f32_e32 v216, s24, v192
	v_fmac_f32_e32 v217, s24, v193
	v_fmac_f32_e32 v218, s24, v194
	v_fmac_f32_e32 v219, s24, v195
	v_fmac_f32_e32 v220, s25, v192
	v_fmac_f32_e32 v221, s25, v193
	v_fmac_f32_e32 v222, s25, v194
	v_fmac_f32_e32 v223, s25, v195
	v_fmac_f32_e32 v224, s26, v192
	v_fmac_f32_e32 v225, s26, v193
	v_fmac_f32_e32 v226, s26, v194
	v_fmac_f32_e32 v227, s26, v195
	v_fmac_f32_e32 v228, s27, v192
	v_fmac_f32_e32 v229, s27, v193
	v_fmac_f32_e32 v230, s27, v194
	v_fmac_f32_e32 v231, s27, v195
	v_readlane_b32 s24, v189, 11
	v_readlane_b32 s25, v189, 27
	v_readlane_b32 s26, v189, 43
	v_readlane_b32 s27, v189, 59
	v_fmac_f32_e32 v216, s24, v196
	v_fmac_f32_e32 v217, s24, v197
	v_fmac_f32_e32 v218, s24, v198
	v_fmac_f32_e32 v219, s24, v199
	v_fmac_f32_e32 v220, s25, v196
	v_fmac_f32_e32 v221, s25, v197
	v_fmac_f32_e32 v222, s25, v198
	v_fmac_f32_e32 v223, s25, v199
	v_fmac_f32_e32 v224, s26, v196
	v_fmac_f32_e32 v225, s26, v197
	v_fmac_f32_e32 v226, s26, v198
	v_fmac_f32_e32 v227, s26, v199
	v_fmac_f32_e32 v228, s27, v196
	v_fmac_f32_e32 v229, s27, v197
	v_fmac_f32_e32 v230, s27, v198
	v_fmac_f32_e32 v231, s27, v199
	v_readlane_b32 s24, v189, 12
	v_readlane_b32 s25, v189, 28
	v_readlane_b32 s26, v189, 44
	v_readlane_b32 s27, v189, 60
	v_fmac_f32_e32 v216, s24, v200
	v_fmac_f32_e32 v217, s24, v201
	v_fmac_f32_e32 v218, s24, v202
	v_fmac_f32_e32 v219, s24, v203
	v_fmac_f32_e32 v220, s25, v200
	v_fmac_f32_e32 v221, s25, v201
	v_fmac_f32_e32 v222, s25, v202
	v_fmac_f32_e32 v223, s25, v203
	v_fmac_f32_e32 v224, s26, v200
	v_fmac_f32_e32 v225, s26, v201
	v_fmac_f32_e32 v226, s26, v202
	v_fmac_f32_e32 v227, s26, v203
	v_fmac_f32_e32 v228, s27, v200
	v_fmac_f32_e32 v229, s27, v201
	v_fmac_f32_e32 v230, s27, v202
	v_fmac_f32_e32 v231, s27, v203
	v_readlane_b32 s24, v189, 13
	v_readlane_b32 s25, v189, 29
	v_readlane_b32 s26, v189, 45
	v_readlane_b32 s27, v189, 61
	v_fmac_f32_e32 v216, s24, v204
	v_fmac_f32_e32 v217, s24, v205
	v_fmac_f32_e32 v218, s24, v206
	v_fmac_f32_e32 v219, s24, v207
	v_fmac_f32_e32 v220, s25, v204
	v_fmac_f32_e32 v221, s25, v205
	v_fmac_f32_e32 v222, s25, v206
	v_fmac_f32_e32 v223, s25, v207
	v_fmac_f32_e32 v224, s26, v204
	v_fmac_f32_e32 v225, s26, v205
	v_fmac_f32_e32 v226, s26, v206
	v_fmac_f32_e32 v227, s26, v207
	v_fmac_f32_e32 v228, s27, v204
	v_fmac_f32_e32 v229, s27, v205
	v_fmac_f32_e32 v230, s27, v206
	v_fmac_f32_e32 v231, s27, v207
	v_readlane_b32 s24, v189, 14
	v_readlane_b32 s25, v189, 30
	v_readlane_b32 s26, v189, 46
	v_readlane_b32 s27, v189, 62
	v_fmac_f32_e32 v216, s24, v208
	v_fmac_f32_e32 v217, s24, v209
	v_fmac_f32_e32 v218, s24, v210
	v_fmac_f32_e32 v219, s24, v211
	v_fmac_f32_e32 v220, s25, v208
	v_fmac_f32_e32 v221, s25, v209
	v_fmac_f32_e32 v222, s25, v210
	v_fmac_f32_e32 v223, s25, v211
	v_fmac_f32_e32 v224, s26, v208
	v_fmac_f32_e32 v225, s26, v209
	v_fmac_f32_e32 v226, s26, v210
	v_fmac_f32_e32 v227, s26, v211
	v_fmac_f32_e32 v228, s27, v208
	v_fmac_f32_e32 v229, s27, v209
	v_fmac_f32_e32 v230, s27, v210
	v_fmac_f32_e32 v231, s27, v211
	v_readlane_b32 s24, v189, 15
	v_readlane_b32 s25, v189, 31
	v_readlane_b32 s26, v189, 47
	v_readlane_b32 s27, v189, 63
	v_fmac_f32_e32 v216, s24, v212
	v_fmac_f32_e32 v217, s24, v213
	v_fmac_f32_e32 v218, s24, v214
	v_fmac_f32_e32 v219, s24, v215
	v_fmac_f32_e32 v220, s25, v212
	v_fmac_f32_e32 v221, s25, v213
	v_fmac_f32_e32 v222, s25, v214
	v_fmac_f32_e32 v223, s25, v215
	v_fmac_f32_e32 v224, s26, v212
	v_fmac_f32_e32 v225, s26, v213
	v_fmac_f32_e32 v226, s26, v214
	v_fmac_f32_e32 v227, s26, v215
	v_fmac_f32_e32 v228, s27, v212
	v_fmac_f32_e32 v229, s27, v213
	v_fmac_f32_e32 v230, s27, v214
	v_fmac_f32_e32 v231, s27, v215
	s_lshl_b32 s19, s18, 10
	v_add_u32_e32 v248, s19, v0
	s_add_u32 s14, s74, 0x47000
	s_addc_u32 s15, s75, 0
	global_atomic_add_f32 v248, v216, s[14:15]
	global_atomic_add_f32 v248, v217, s[14:15] offset:4
	global_atomic_add_f32 v248, v218, s[14:15] offset:8
	global_atomic_add_f32 v248, v219, s[14:15] offset:12
	s_add_u32 s14, s14, 0x5800
	s_addc_u32 s15, s15, 0
	global_atomic_add_f32 v248, v220, s[14:15]
	global_atomic_add_f32 v248, v221, s[14:15] offset:4
	global_atomic_add_f32 v248, v222, s[14:15] offset:8
	global_atomic_add_f32 v248, v223, s[14:15] offset:12
	s_add_u32 s14, s14, 0x5800
	s_addc_u32 s15, s15, 0
	global_atomic_add_f32 v248, v224, s[14:15]
	global_atomic_add_f32 v248, v225, s[14:15] offset:4
	global_atomic_add_f32 v248, v226, s[14:15] offset:8
	global_atomic_add_f32 v248, v227, s[14:15] offset:12
	s_add_u32 s14, s14, 0x5800
	s_addc_u32 s15, s15, 0
	global_atomic_add_f32 v248, v228, s[14:15]
	global_atomic_add_f32 v248, v229, s[14:15] offset:4
	global_atomic_add_f32 v248, v230, s[14:15] offset:8
	global_atomic_add_f32 v248, v231, s[14:15] offset:12
.Lp1_nob1:
	s_waitcnt vmcnt(12)
	v_pk_add_f32 v[52:53], v[52:53], v[18:19]
	v_pk_add_f32 v[54:55], v[54:55], v[18:19]
	v_pk_add_f32 v[56:57], v[56:57], v[18:19]
	v_pk_add_f32 v[58:59], v[58:59], v[18:19]
	v_pk_add_f32 v[60:61], v[60:61], v[18:19]
	v_pk_add_f32 v[62:63], v[62:63], v[18:19]
	v_pk_add_f32 v[64:65], v[64:65], v[18:19]
	v_pk_add_f32 v[66:67], v[66:67], v[18:19]
	s_add_u32 s14, s12, 0x6000
	s_addc_u32 s15, s13, 0
	s_add_u32 s16, s14, 0x1000
	s_addc_u32 s17, s15, 0
	global_load_dwordx4 v[148:151], v0, s[14:15]
	global_load_dwordx4 v[152:155], v0, s[14:15] offset:1024
	global_load_dwordx4 v[156:159], v0, s[14:15] offset:2048
	global_load_dwordx4 v[160:163], v0, s[14:15] offset:3072
	global_load_dwordx4 v[164:167], v0, s[16:17]
	global_load_dwordx4 v[168:171], v0, s[16:17] offset:1024
	global_load_dwordx4 v[172:175], v0, s[16:17] offset:2048
	global_load_dwordx4 v[176:179], v0, s[16:17] offset:3072
	v_pk_mul_f32 v[4:5], v[68:69], v[68:69]
	v_pk_fma_f32 v[4:5], v[70:71], v[70:71], v[4:5]
	v_pk_fma_f32 v[4:5], v[72:73], v[72:73], v[4:5]
	v_pk_fma_f32 v[4:5], v[74:75], v[74:75], v[4:5]
	v_pk_fma_f32 v[4:5], v[76:77], v[76:77], v[4:5]
	v_pk_fma_f32 v[4:5], v[78:79], v[78:79], v[4:5]
	v_pk_fma_f32 v[4:5], v[80:81], v[80:81], v[4:5]
	v_pk_fma_f32 v[4:5], v[82:83], v[82:83], v[4:5]
	v_add_f32_e32 v4, v4, v5
	s_nop 1
	v_add_f32_dpp v4, v4, v4 quad_perm:[1,0,3,2] row_mask:0xf bank_mask:0xf
	s_nop 1
	v_add_f32_dpp v4, v4, v4 quad_perm:[2,3,0,1] row_mask:0xf bank_mask:0xf
	s_nop 1
	v_add_f32_dpp v4, v4, v4 row_half_mirror row_mask:0xf bank_mask:0xf
	s_nop 1
	v_add_f32_dpp v4, v4, v4 row_mirror row_mask:0xf bank_mask:0xf
	s_nop 1
	v_add_f32_dpp v4, v4, v4 row_bcast:15 row_mask:0xa bank_mask:0xf
	s_nop 1
	v_add_f32_dpp v4, v4, v4 row_bcast:31 row_mask:0xc bank_mask:0xf
	s_nop 1
	v_readlane_b32 s20, v4, 63
	s_nop 1
	v_fma_f32 v6, s20, v16, v17
	v_rsq_f32_e32 v6, v6
	s_nop 0
	v_pk_mul_f32 v[68:69], v[68:69], v[6:7] op_sel_hi:[1,0]
	v_pk_mul_f32 v[70:71], v[70:71], v[6:7] op_sel_hi:[1,0]
	v_pk_mul_f32 v[72:73], v[72:73], v[6:7] op_sel_hi:[1,0]
	v_pk_mul_f32 v[74:75], v[74:75], v[6:7] op_sel_hi:[1,0]
	v_pk_mul_f32 v[76:77], v[76:77], v[6:7] op_sel_hi:[1,0]
	v_pk_mul_f32 v[78:79], v[78:79], v[6:7] op_sel_hi:[1,0]
	v_pk_mul_f32 v[80:81], v[80:81], v[6:7] op_sel_hi:[1,0]
	v_pk_mul_f32 v[82:83], v[82:83], v[6:7] op_sel_hi:[1,0]
	v_pk_mul_f32 v[68:69], v[68:69], v[20:21]
	v_pk_mul_f32 v[70:71], v[70:71], v[22:23]
	v_pk_mul_f32 v[72:73], v[72:73], v[24:25]
	v_pk_mul_f32 v[74:75], v[74:75], v[26:27]
	v_pk_mul_f32 v[76:77], v[76:77], v[28:29]
	v_pk_mul_f32 v[78:79], v[78:79], v[30:31]
	v_pk_mul_f32 v[80:81], v[80:81], v[32:33]
	v_pk_mul_f32 v[82:83], v[82:83], v[34:35]
	v_pk_fma_f32 v[68:69], v[68:69], v[52:53], v[36:37]
	v_pk_fma_f32 v[70:71], v[70:71], v[54:55], v[38:39]
	v_pk_fma_f32 v[72:73], v[72:73], v[56:57], v[40:41]
	v_pk_fma_f32 v[74:75], v[74:75], v[58:59], v[42:43]
	v_pk_fma_f32 v[76:77], v[76:77], v[60:61], v[44:45]
	v_pk_fma_f32 v[78:79], v[78:79], v[62:63], v[46:47]
	v_pk_fma_f32 v[80:81], v[80:81], v[64:65], v[48:49]
	v_pk_fma_f32 v[82:83], v[82:83], v[66:67], v[50:51]
	v_cvt_pk_bf16_f32 v232, v68, v69
	v_cvt_pk_bf16_f32 v233, v70, v71
	v_cvt_pk_bf16_f32 v234, v72, v73
	v_cvt_pk_bf16_f32 v235, v74, v75
	v_cvt_pk_bf16_f32 v236, v76, v77
	v_cvt_pk_bf16_f32 v237, v78, v79
	v_cvt_pk_bf16_f32 v238, v80, v81
	v_cvt_pk_bf16_f32 v239, v82, v83
	global_store_dwordx2 v1, v[232:233], s[10:11]
	global_store_dwordx2 v1, v[234:235], s[10:11] offset:512
	global_store_dwordx2 v1, v[236:237], s[10:11] offset:1024
	global_store_dwordx2 v1, v[238:239], s[10:11] offset:1536
	s_add_u32 s10, s10, 0x400000
	s_addc_u32 s11, s11, 0
	global_load_dwordx4 v[68:71], v0, s[8:9]
	global_load_dwordx4 v[72:75], v0, s[8:9] offset:1024
	global_load_dwordx4 v[76:79], v0, s[8:9] offset:2048
	global_load_dwordx4 v[80:83], v0, s[8:9] offset:3072
	s_add_u32 s8, s8, 0x800000
	s_addc_u32 s9, s9, 0
	s_waitcnt vmcnt(24)
	v_pk_mul_f32 v[4:5], v[84:85], v[84:85]
	v_pk_fma_f32 v[4:5], v[86:87], v[86:87], v[4:5]
	v_pk_fma_f32 v[4:5], v[88:89], v[88:89], v[4:5]
	v_pk_fma_f32 v[4:5], v[90:91], v[90:91], v[4:5]
	v_pk_fma_f32 v[4:5], v[92:93], v[92:93], v[4:5]
	v_pk_fma_f32 v[4:5], v[94:95], v[94:95], v[4:5]
	v_pk_fma_f32 v[4:5], v[96:97], v[96:97], v[4:5]
	v_pk_fma_f32 v[4:5], v[98:99], v[98:99], v[4:5]
	v_add_f32_e32 v4, v4, v5
	s_nop 1
	v_add_f32_dpp v4, v4, v4 quad_perm:[1,0,3,2] row_mask:0xf bank_mask:0xf
	s_nop 1
	v_add_f32_dpp v4, v4, v4 quad_perm:[2,3,0,1] row_mask:0xf bank_mask:0xf
	s_nop 1
	v_add_f32_dpp v4, v4, v4 row_half_mirror row_mask:0xf bank_mask:0xf
	s_nop 1
	v_add_f32_dpp v4, v4, v4 row_mirror row_mask:0xf bank_mask:0xf
	s_nop 1
	v_add_f32_dpp v4, v4, v4 row_bcast:15 row_mask:0xa bank_mask:0xf
	s_nop 1
	v_add_f32_dpp v4, v4, v4 row_bcast:31 row_mask:0xc bank_mask:0xf
	s_nop 1
	v_readlane_b32 s20, v4, 63
	s_nop 1
	v_fma_f32 v6, s20, v16, v17
	v_rsq_f32_e32 v6, v6
	s_nop 0
	v_pk_mul_f32 v[84:85], v[84:85], v[6:7] op_sel_hi:[1,0]
	v_pk_mul_f32 v[86:87], v[86:87], v[6:7] op_sel_hi:[1,0]
	v_pk_mul_f32 v[88:89], v[88:89], v[6:7] op_sel_hi:[1,0]
	v_pk_mul_f32 v[90:91], v[90:91], v[6:7] op_sel_hi:[1,0]
	v_pk_mul_f32 v[92:93], v[92:93], v[6:7] op_sel_hi:[1,0]
	v_pk_mul_f32 v[94:95], v[94:95], v[6:7] op_sel_hi:[1,0]
	v_pk_mul_f32 v[96:97], v[96:97], v[6:7] op_sel_hi:[1,0]
	v_pk_mul_f32 v[98:99], v[98:99], v[6:7] op_sel_hi:[1,0]
	v_pk_mul_f32 v[84:85], v[84:85], v[20:21]
	v_pk_mul_f32 v[86:87], v[86:87], v[22:23]
	v_pk_mul_f32 v[88:89], v[88:89], v[24:25]
	v_pk_mul_f32 v[90:91], v[90:91], v[26:27]
	v_pk_mul_f32 v[92:93], v[92:93], v[28:29]
	v_pk_mul_f32 v[94:95], v[94:95], v[30:31]
	v_pk_mul_f32 v[96:97], v[96:97], v[32:33]
	v_pk_mul_f32 v[98:99], v[98:99], v[34:35]
	v_pk_fma_f32 v[84:85], v[84:85], v[52:53], v[36:37]
	v_pk_fma_f32 v[86:87], v[86:87], v[54:55], v[38:39]
	v_pk_fma_f32 v[88:89], v[88:89], v[56:57], v[40:41]
	v_pk_fma_f32 v[90:91], v[90:91], v[58:59], v[42:43]
	v_pk_fma_f32 v[92:93], v[92:93], v[60:61], v[44:45]
	v_pk_fma_f32 v[94:95], v[94:95], v[62:63], v[46:47]
	v_pk_fma_f32 v[96:97], v[96:97], v[64:65], v[48:49]
	v_pk_fma_f32 v[98:99], v[98:99], v[66:67], v[50:51]
	v_cvt_pk_bf16_f32 v240, v84, v85
	v_cvt_pk_bf16_f32 v241, v86, v87
	v_cvt_pk_bf16_f32 v242, v88, v89
	v_cvt_pk_bf16_f32 v243, v90, v91
	v_cvt_pk_bf16_f32 v244, v92, v93
	v_cvt_pk_bf16_f32 v245, v94, v95
	v_cvt_pk_bf16_f32 v246, v96, v97
	v_cvt_pk_bf16_f32 v247, v98, v99
	global_store_dwordx2 v1, v[240:241], s[10:11]
	global_store_dwordx2 v1, v[242:243], s[10:11] offset:512
	global_store_dwordx2 v1, v[244:245], s[10:11] offset:1024
	global_store_dwordx2 v1, v[246:247], s[10:11] offset:1536
	s_add_u32 s10, s10, 0x400000
	s_addc_u32 s11, s11, 0
	global_load_dwordx4 v[84:87], v0, s[8:9]
	global_load_dwordx4 v[88:91], v0, s[8:9] offset:1024
	global_load_dwordx4 v[92:95], v0, s[8:9] offset:2048
	global_load_dwordx4 v[96:99], v0, s[8:9] offset:3072
	s_add_u32 s8, s8, 0x800000
	s_addc_u32 s9, s9, 0
	s_waitcnt vmcnt(28)
	v_pk_mul_f32 v[4:5], v[100:101], v[100:101]
	v_pk_fma_f32 v[4:5], v[102:103], v[102:103], v[4:5]
	v_pk_fma_f32 v[4:5], v[104:105], v[104:105], v[4:5]
	v_pk_fma_f32 v[4:5], v[106:107], v[106:107], v[4:5]
	v_pk_fma_f32 v[4:5], v[108:109], v[108:109], v[4:5]
	v_pk_fma_f32 v[4:5], v[110:111], v[110:111], v[4:5]
	v_pk_fma_f32 v[4:5], v[112:113], v[112:113], v[4:5]
	v_pk_fma_f32 v[4:5], v[114:115], v[114:115], v[4:5]
	v_add_f32_e32 v4, v4, v5
	s_nop 1
	v_add_f32_dpp v4, v4, v4 quad_perm:[1,0,3,2] row_mask:0xf bank_mask:0xf
	s_nop 1
	v_add_f32_dpp v4, v4, v4 quad_perm:[2,3,0,1] row_mask:0xf bank_mask:0xf
	s_nop 1
	v_add_f32_dpp v4, v4, v4 row_half_mirror row_mask:0xf bank_mask:0xf
	s_nop 1
	v_add_f32_dpp v4, v4, v4 row_mirror row_mask:0xf bank_mask:0xf
	s_nop 1
	v_add_f32_dpp v4, v4, v4 row_bcast:15 row_mask:0xa bank_mask:0xf
	s_nop 1
	v_add_f32_dpp v4, v4, v4 row_bcast:31 row_mask:0xc bank_mask:0xf
	s_nop 1
	v_readlane_b32 s20, v4, 63
	s_nop 1
	v_fma_f32 v6, s20, v16, v17
	v_rsq_f32_e32 v6, v6
	s_nop 0
	v_pk_mul_f32 v[100:101], v[100:101], v[6:7] op_sel_hi:[1,0]
	v_pk_mul_f32 v[102:103], v[102:103], v[6:7] op_sel_hi:[1,0]
	v_pk_mul_f32 v[104:105], v[104:105], v[6:7] op_sel_hi:[1,0]
	v_pk_mul_f32 v[106:107], v[106:107], v[6:7] op_sel_hi:[1,0]
	v_pk_mul_f32 v[108:109], v[108:109], v[6:7] op_sel_hi:[1,0]
	v_pk_mul_f32 v[110:111], v[110:111], v[6:7] op_sel_hi:[1,0]
	v_pk_mul_f32 v[112:113], v[112:113], v[6:7] op_sel_hi:[1,0]
	v_pk_mul_f32 v[114:115], v[114:115], v[6:7] op_sel_hi:[1,0]
	v_pk_mul_f32 v[100:101], v[100:101], v[20:21]
	v_pk_mul_f32 v[102:103], v[102:103], v[22:23]
	v_pk_mul_f32 v[104:105], v[104:105], v[24:25]
	v_pk_mul_f32 v[106:107], v[106:107], v[26:27]
	v_pk_mul_f32 v[108:109], v[108:109], v[28:29]
	v_pk_mul_f32 v[110:111], v[110:111], v[30:31]
	v_pk_mul_f32 v[112:113], v[112:113], v[32:33]
	v_pk_mul_f32 v[114:115], v[114:115], v[34:35]
	v_pk_fma_f32 v[100:101], v[100:101], v[52:53], v[36:37]
	v_pk_fma_f32 v[102:103], v[102:103], v[54:55], v[38:39]
	v_pk_fma_f32 v[104:105], v[104:105], v[56:57], v[40:41]
	v_pk_fma_f32 v[106:107], v[106:107], v[58:59], v[42:43]
	v_pk_fma_f32 v[108:109], v[108:109], v[60:61], v[44:45]
	v_pk_fma_f32 v[110:111], v[110:111], v[62:63], v[46:47]
	v_pk_fma_f32 v[112:113], v[112:113], v[64:65], v[48:49]
	v_pk_fma_f32 v[114:115], v[114:115], v[66:67], v[50:51]
	v_cvt_pk_bf16_f32 v232, v100, v101
	v_cvt_pk_bf16_f32 v233, v102, v103
	v_cvt_pk_bf16_f32 v234, v104, v105
	v_cvt_pk_bf16_f32 v235, v106, v107
	v_cvt_pk_bf16_f32 v236, v108, v109
	v_cvt_pk_bf16_f32 v237, v110, v111
	v_cvt_pk_bf16_f32 v238, v112, v113
	v_cvt_pk_bf16_f32 v239, v114, v115
	global_store_dwordx2 v1, v[232:233], s[10:11]
	global_store_dwordx2 v1, v[234:235], s[10:11] offset:512
	global_store_dwordx2 v1, v[236:237], s[10:11] offset:1024
	global_store_dwordx2 v1, v[238:239], s[10:11] offset:1536
	s_add_u32 s10, s10, 0x400000
	s_addc_u32 s11, s11, 0
	global_load_dwordx4 v[100:103], v0, s[8:9]
	global_load_dwordx4 v[104:107], v0, s[8:9] offset:1024
	global_load_dwordx4 v[108:111], v0, s[8:9] offset:2048
	global_load_dwordx4 v[112:115], v0, s[8:9] offset:3072
	s_add_u32 s8, s8, 0x800000
	s_addc_u32 s9, s9, 0
	s_waitcnt vmcnt(32)
	v_pk_mul_f32 v[4:5], v[116:117], v[116:117]
	v_pk_fma_f32 v[4:5], v[118:119], v[118:119], v[4:5]
	v_pk_fma_f32 v[4:5], v[120:121], v[120:121], v[4:5]
	v_pk_fma_f32 v[4:5], v[122:123], v[122:123], v[4:5]
	v_pk_fma_f32 v[4:5], v[124:125], v[124:125], v[4:5]
	v_pk_fma_f32 v[4:5], v[126:127], v[126:127], v[4:5]
	v_pk_fma_f32 v[4:5], v[128:129], v[128:129], v[4:5]
	v_pk_fma_f32 v[4:5], v[130:131], v[130:131], v[4:5]
	v_add_f32_e32 v4, v4, v5
	s_nop 1
	v_add_f32_dpp v4, v4, v4 quad_perm:[1,0,3,2] row_mask:0xf bank_mask:0xf
	s_nop 1
	v_add_f32_dpp v4, v4, v4 quad_perm:[2,3,0,1] row_mask:0xf bank_mask:0xf
	s_nop 1
	v_add_f32_dpp v4, v4, v4 row_half_mirror row_mask:0xf bank_mask:0xf
	s_nop 1
	v_add_f32_dpp v4, v4, v4 row_mirror row_mask:0xf bank_mask:0xf
	s_nop 1
	v_add_f32_dpp v4, v4, v4 row_bcast:15 row_mask:0xa bank_mask:0xf
	s_nop 1
	v_add_f32_dpp v4, v4, v4 row_bcast:31 row_mask:0xc bank_mask:0xf
	s_nop 1
	v_readlane_b32 s20, v4, 63
	s_nop 1
	v_fma_f32 v6, s20, v16, v17
	v_rsq_f32_e32 v6, v6
	s_nop 0
	v_pk_mul_f32 v[116:117], v[116:117], v[6:7] op_sel_hi:[1,0]
	v_pk_mul_f32 v[118:119], v[118:119], v[6:7] op_sel_hi:[1,0]
	v_pk_mul_f32 v[120:121], v[120:121], v[6:7] op_sel_hi:[1,0]
	v_pk_mul_f32 v[122:123], v[122:123], v[6:7] op_sel_hi:[1,0]
	v_pk_mul_f32 v[124:125], v[124:125], v[6:7] op_sel_hi:[1,0]
	v_pk_mul_f32 v[126:127], v[126:127], v[6:7] op_sel_hi:[1,0]
	v_pk_mul_f32 v[128:129], v[128:129], v[6:7] op_sel_hi:[1,0]
	v_pk_mul_f32 v[130:131], v[130:131], v[6:7] op_sel_hi:[1,0]
	v_pk_mul_f32 v[116:117], v[116:117], v[20:21]
	v_pk_mul_f32 v[118:119], v[118:119], v[22:23]
	v_pk_mul_f32 v[120:121], v[120:121], v[24:25]
	v_pk_mul_f32 v[122:123], v[122:123], v[26:27]
	v_pk_mul_f32 v[124:125], v[124:125], v[28:29]
	v_pk_mul_f32 v[126:127], v[126:127], v[30:31]
	v_pk_mul_f32 v[128:129], v[128:129], v[32:33]
	v_pk_mul_f32 v[130:131], v[130:131], v[34:35]
	v_pk_fma_f32 v[116:117], v[116:117], v[52:53], v[36:37]
	v_pk_fma_f32 v[118:119], v[118:119], v[54:55], v[38:39]
	v_pk_fma_f32 v[120:121], v[120:121], v[56:57], v[40:41]
	v_pk_fma_f32 v[122:123], v[122:123], v[58:59], v[42:43]
	v_pk_fma_f32 v[124:125], v[124:125], v[60:61], v[44:45]
	v_pk_fma_f32 v[126:127], v[126:127], v[62:63], v[46:47]
	v_pk_fma_f32 v[128:129], v[128:129], v[64:65], v[48:49]
	v_pk_fma_f32 v[130:131], v[130:131], v[66:67], v[50:51]
	v_cvt_pk_bf16_f32 v240, v116, v117
	v_cvt_pk_bf16_f32 v241, v118, v119
	v_cvt_pk_bf16_f32 v242, v120, v121
	v_cvt_pk_bf16_f32 v243, v122, v123
	v_cvt_pk_bf16_f32 v244, v124, v125
	v_cvt_pk_bf16_f32 v245, v126, v127
	v_cvt_pk_bf16_f32 v246, v128, v129
	v_cvt_pk_bf16_f32 v247, v130, v131
	global_store_dwordx2 v1, v[240:241], s[10:11]
	global_store_dwordx2 v1, v[242:243], s[10:11] offset:512
	global_store_dwordx2 v1, v[244:245], s[10:11] offset:1024
	global_store_dwordx2 v1, v[246:247], s[10:11] offset:1536
	s_add_u32 s10, s10, 0x400000
	s_addc_u32 s11, s11, 0
	global_load_dwordx4 v[116:119], v0, s[8:9]
	global_load_dwordx4 v[120:123], v0, s[8:9] offset:1024
	global_load_dwordx4 v[124:127], v0, s[8:9] offset:2048
	global_load_dwordx4 v[128:131], v0, s[8:9] offset:3072
	s_add_u32 s8, s8, 0x800000
	s_addc_u32 s9, s9, 0
	s_waitcnt vmcnt(24)
	v_pk_add_f32 v[164:165], v[164:165], v[18:19]
	v_pk_add_f32 v[166:167], v[166:167], v[18:19]
	v_pk_add_f32 v[168:169], v[168:169], v[18:19]
	v_pk_add_f32 v[170:171], v[170:171], v[18:19]
	v_pk_add_f32 v[172:173], v[172:173], v[18:19]
	v_pk_add_f32 v[174:175], v[174:175], v[18:19]
	v_pk_add_f32 v[176:177], v[176:177], v[18:19]
	v_pk_add_f32 v[178:179], v[178:179], v[18:19]
	s_add_u32 s14, s12, 0xc000
	s_addc_u32 s15, s13, 0
	s_add_u32 s16, s14, 0x1000
	s_addc_u32 s17, s15, 0
	global_load_dwordx4 v[36:39], v0, s[14:15]
	global_load_dwordx4 v[40:43], v0, s[14:15] offset:1024
	global_load_dwordx4 v[44:47], v0, s[14:15] offset:2048
	global_load_dwordx4 v[48:51], v0, s[14:15] offset:3072
	global_load_dwordx4 v[52:55], v0, s[16:17]
	global_load_dwordx4 v[56:59], v0, s[16:17] offset:1024
	global_load_dwordx4 v[60:63], v0, s[16:17] offset:2048
	global_load_dwordx4 v[64:67], v0, s[16:17] offset:3072
	v_pk_mul_f32 v[4:5], v[68:69], v[68:69]
	v_pk_fma_f32 v[4:5], v[70:71], v[70:71], v[4:5]
	v_pk_fma_f32 v[4:5], v[72:73], v[72:73], v[4:5]
	v_pk_fma_f32 v[4:5], v[74:75], v[74:75], v[4:5]
	v_pk_fma_f32 v[4:5], v[76:77], v[76:77], v[4:5]
	v_pk_fma_f32 v[4:5], v[78:79], v[78:79], v[4:5]
	v_pk_fma_f32 v[4:5], v[80:81], v[80:81], v[4:5]
	v_pk_fma_f32 v[4:5], v[82:83], v[82:83], v[4:5]
	v_add_f32_e32 v4, v4, v5
	s_nop 1
	v_add_f32_dpp v4, v4, v4 quad_perm:[1,0,3,2] row_mask:0xf bank_mask:0xf
	s_nop 1
	v_add_f32_dpp v4, v4, v4 quad_perm:[2,3,0,1] row_mask:0xf bank_mask:0xf
	s_nop 1
	v_add_f32_dpp v4, v4, v4 row_half_mirror row_mask:0xf bank_mask:0xf
	s_nop 1
	v_add_f32_dpp v4, v4, v4 row_mirror row_mask:0xf bank_mask:0xf
	s_nop 1
	v_add_f32_dpp v4, v4, v4 row_bcast:15 row_mask:0xa bank_mask:0xf
	s_nop 1
	v_add_f32_dpp v4, v4, v4 row_bcast:31 row_mask:0xc bank_mask:0xf
	s_nop 1
	v_readlane_b32 s20, v4, 63
	s_nop 1
	v_fma_f32 v6, s20, v16, v17
	v_rsq_f32_e32 v6, v6
	s_nop 0
	v_pk_mul_f32 v[68:69], v[68:69], v[6:7] op_sel_hi:[1,0]
	v_pk_mul_f32 v[70:71], v[70:71], v[6:7] op_sel_hi:[1,0]
	v_pk_mul_f32 v[72:73], v[72:73], v[6:7] op_sel_hi:[1,0]
	v_pk_mul_f32 v[74:75], v[74:75], v[6:7] op_sel_hi:[1,0]
	v_pk_mul_f32 v[76:77], v[76:77], v[6:7] op_sel_hi:[1,0]
	v_pk_mul_f32 v[78:79], v[78:79], v[6:7] op_sel_hi:[1,0]
	v_pk_mul_f32 v[80:81], v[80:81], v[6:7] op_sel_hi:[1,0]
	v_pk_mul_f32 v[82:83], v[82:83], v[6:7] op_sel_hi:[1,0]
	v_pk_mul_f32 v[68:69], v[68:69], v[20:21]
	v_pk_mul_f32 v[70:71], v[70:71], v[22:23]
	v_pk_mul_f32 v[72:73], v[72:73], v[24:25]
	v_pk_mul_f32 v[74:75], v[74:75], v[26:27]
	v_pk_mul_f32 v[76:77], v[76:77], v[28:29]
	v_pk_mul_f32 v[78:79], v[78:79], v[30:31]
	v_pk_mul_f32 v[80:81], v[80:81], v[32:33]
	v_pk_mul_f32 v[82:83], v[82:83], v[34:35]
	v_pk_fma_f32 v[68:69], v[68:69], v[164:165], v[148:149]
	v_pk_fma_f32 v[70:71], v[70:71], v[166:167], v[150:151]
	v_pk_fma_f32 v[72:73], v[72:73], v[168:169], v[152:153]
	v_pk_fma_f32 v[74:75], v[74:75], v[170:171], v[154:155]
	v_pk_fma_f32 v[76:77], v[76:77], v[172:173], v[156:157]
	v_pk_fma_f32 v[78:79], v[78:79], v[174:175], v[158:159]
	v_pk_fma_f32 v[80:81], v[80:81], v[176:177], v[160:161]
	v_pk_fma_f32 v[82:83], v[82:83], v[178:179], v[162:163]
	v_cvt_pk_bf16_f32 v232, v68, v69
	v_cvt_pk_bf16_f32 v233, v70, v71
	v_cvt_pk_bf16_f32 v234, v72, v73
	v_cvt_pk_bf16_f32 v235, v74, v75
	v_cvt_pk_bf16_f32 v236, v76, v77
	v_cvt_pk_bf16_f32 v237, v78, v79
	v_cvt_pk_bf16_f32 v238, v80, v81
	v_cvt_pk_bf16_f32 v239, v82, v83
	global_store_dwordx2 v1, v[232:233], s[10:11]
	global_store_dwordx2 v1, v[234:235], s[10:11] offset:512
	global_store_dwordx2 v1, v[236:237], s[10:11] offset:1024
	global_store_dwordx2 v1, v[238:239], s[10:11] offset:1536
	s_add_u32 s10, s10, 0x400000
	s_addc_u32 s11, s11, 0
	global_load_dwordx4 v[68:71], v0, s[8:9]
	global_load_dwordx4 v[72:75], v0, s[8:9] offset:1024
	global_load_dwordx4 v[76:79], v0, s[8:9] offset:2048
	global_load_dwordx4 v[80:83], v0, s[8:9] offset:3072
	s_add_u32 s8, s8, 0x800000
	s_addc_u32 s9, s9, 0
	s_waitcnt vmcnt(32)
	v_pk_mul_f32 v[4:5], v[84:85], v[84:85]
	v_pk_fma_f32 v[4:5], v[86:87], v[86:87], v[4:5]
	v_pk_fma_f32 v[4:5], v[88:89], v[88:89], v[4:5]
	v_pk_fma_f32 v[4:5], v[90:91], v[90:91], v[4:5]
	v_pk_fma_f32 v[4:5], v[92:93], v[92:93], v[4:5]
	v_pk_fma_f32 v[4:5], v[94:95], v[94:95], v[4:5]
	v_pk_fma_f32 v[4:5], v[96:97], v[96:97], v[4:5]
	v_pk_fma_f32 v[4:5], v[98:99], v[98:99], v[4:5]
	v_add_f32_e32 v4, v4, v5
	s_nop 1
	v_add_f32_dpp v4, v4, v4 quad_perm:[1,0,3,2] row_mask:0xf bank_mask:0xf
	s_nop 1
	v_add_f32_dpp v4, v4, v4 quad_perm:[2,3,0,1] row_mask:0xf bank_mask:0xf
	s_nop 1
	v_add_f32_dpp v4, v4, v4 row_half_mirror row_mask:0xf bank_mask:0xf
	s_nop 1
	v_add_f32_dpp v4, v4, v4 row_mirror row_mask:0xf bank_mask:0xf
	s_nop 1
	v_add_f32_dpp v4, v4, v4 row_bcast:15 row_mask:0xa bank_mask:0xf
	s_nop 1
	v_add_f32_dpp v4, v4, v4 row_bcast:31 row_mask:0xc bank_mask:0xf
	s_nop 1
	v_readlane_b32 s20, v4, 63
	s_nop 1
	v_fma_f32 v6, s20, v16, v17
	v_rsq_f32_e32 v6, v6
	s_nop 0
	v_pk_mul_f32 v[84:85], v[84:85], v[6:7] op_sel_hi:[1,0]
	v_pk_mul_f32 v[86:87], v[86:87], v[6:7] op_sel_hi:[1,0]
	v_pk_mul_f32 v[88:89], v[88:89], v[6:7] op_sel_hi:[1,0]
	v_pk_mul_f32 v[90:91], v[90:91], v[6:7] op_sel_hi:[1,0]
	v_pk_mul_f32 v[92:93], v[92:93], v[6:7] op_sel_hi:[1,0]
	v_pk_mul_f32 v[94:95], v[94:95], v[6:7] op_sel_hi:[1,0]
	v_pk_mul_f32 v[96:97], v[96:97], v[6:7] op_sel_hi:[1,0]
	v_pk_mul_f32 v[98:99], v[98:99], v[6:7] op_sel_hi:[1,0]
	v_pk_mul_f32 v[84:85], v[84:85], v[20:21]
	v_pk_mul_f32 v[86:87], v[86:87], v[22:23]
	v_pk_mul_f32 v[88:89], v[88:89], v[24:25]
	v_pk_mul_f32 v[90:91], v[90:91], v[26:27]
	v_pk_mul_f32 v[92:93], v[92:93], v[28:29]
	v_pk_mul_f32 v[94:95], v[94:95], v[30:31]
	v_pk_mul_f32 v[96:97], v[96:97], v[32:33]
	v_pk_mul_f32 v[98:99], v[98:99], v[34:35]
	v_pk_fma_f32 v[84:85], v[84:85], v[164:165], v[148:149]
	v_pk_fma_f32 v[86:87], v[86:87], v[166:167], v[150:151]
	v_pk_fma_f32 v[88:89], v[88:89], v[168:169], v[152:153]
	v_pk_fma_f32 v[90:91], v[90:91], v[170:171], v[154:155]
	v_pk_fma_f32 v[92:93], v[92:93], v[172:173], v[156:157]
	v_pk_fma_f32 v[94:95], v[94:95], v[174:175], v[158:159]
	v_pk_fma_f32 v[96:97], v[96:97], v[176:177], v[160:161]
	v_pk_fma_f32 v[98:99], v[98:99], v[178:179], v[162:163]
	v_cvt_pk_bf16_f32 v240, v84, v85
	v_cvt_pk_bf16_f32 v241, v86, v87
	v_cvt_pk_bf16_f32 v242, v88, v89
	v_cvt_pk_bf16_f32 v243, v90, v91
	v_cvt_pk_bf16_f32 v244, v92, v93
	v_cvt_pk_bf16_f32 v245, v94, v95
	v_cvt_pk_bf16_f32 v246, v96, v97
	v_cvt_pk_bf16_f32 v247, v98, v99
	global_store_dwordx2 v1, v[240:241], s[10:11]
	global_store_dwordx2 v1, v[242:243], s[10:11] offset:512
	global_store_dwordx2 v1, v[244:245], s[10:11] offset:1024
	global_store_dwordx2 v1, v[246:247], s[10:11] offset:1536
	s_add_u32 s10, s10, 0x400000
	s_addc_u32 s11, s11, 0
	global_load_dwordx4 v[84:87], v0, s[8:9]
	global_load_dwordx4 v[88:91], v0, s[8:9] offset:1024
	global_load_dwordx4 v[92:95], v0, s[8:9] offset:2048
	global_load_dwordx4 v[96:99], v0, s[8:9] offset:3072
	s_add_u32 s8, s8, 0x800000
	s_addc_u32 s9, s9, 0
	s_waitcnt vmcnt(32)
	v_pk_mul_f32 v[4:5], v[100:101], v[100:101]
	v_pk_fma_f32 v[4:5], v[102:103], v[102:103], v[4:5]
	v_pk_fma_f32 v[4:5], v[104:105], v[104:105], v[4:5]
	v_pk_fma_f32 v[4:5], v[106:107], v[106:107], v[4:5]
	v_pk_fma_f32 v[4:5], v[108:109], v[108:109], v[4:5]
	v_pk_fma_f32 v[4:5], v[110:111], v[110:111], v[4:5]
	v_pk_fma_f32 v[4:5], v[112:113], v[112:113], v[4:5]
	v_pk_fma_f32 v[4:5], v[114:115], v[114:115], v[4:5]
	v_add_f32_e32 v4, v4, v5
	s_nop 1
	v_add_f32_dpp v4, v4, v4 quad_perm:[1,0,3,2] row_mask:0xf bank_mask:0xf
	s_nop 1
	v_add_f32_dpp v4, v4, v4 quad_perm:[2,3,0,1] row_mask:0xf bank_mask:0xf
	s_nop 1
	v_add_f32_dpp v4, v4, v4 row_half_mirror row_mask:0xf bank_mask:0xf
	s_nop 1
	v_add_f32_dpp v4, v4, v4 row_mirror row_mask:0xf bank_mask:0xf
	s_nop 1
	v_add_f32_dpp v4, v4, v4 row_bcast:15 row_mask:0xa bank_mask:0xf
	s_nop 1
	v_add_f32_dpp v4, v4, v4 row_bcast:31 row_mask:0xc bank_mask:0xf
	s_nop 1
	v_readlane_b32 s20, v4, 63
	s_nop 1
	v_fma_f32 v6, s20, v16, v17
	v_rsq_f32_e32 v6, v6
	s_nop 0
	v_pk_mul_f32 v[100:101], v[100:101], v[6:7] op_sel_hi:[1,0]
	v_pk_mul_f32 v[102:103], v[102:103], v[6:7] op_sel_hi:[1,0]
	v_pk_mul_f32 v[104:105], v[104:105], v[6:7] op_sel_hi:[1,0]
	v_pk_mul_f32 v[106:107], v[106:107], v[6:7] op_sel_hi:[1,0]
	v_pk_mul_f32 v[108:109], v[108:109], v[6:7] op_sel_hi:[1,0]
	v_pk_mul_f32 v[110:111], v[110:111], v[6:7] op_sel_hi:[1,0]
	v_pk_mul_f32 v[112:113], v[112:113], v[6:7] op_sel_hi:[1,0]
	v_pk_mul_f32 v[114:115], v[114:115], v[6:7] op_sel_hi:[1,0]
	v_pk_mul_f32 v[100:101], v[100:101], v[20:21]
	v_pk_mul_f32 v[102:103], v[102:103], v[22:23]
	v_pk_mul_f32 v[104:105], v[104:105], v[24:25]
	v_pk_mul_f32 v[106:107], v[106:107], v[26:27]
	v_pk_mul_f32 v[108:109], v[108:109], v[28:29]
	v_pk_mul_f32 v[110:111], v[110:111], v[30:31]
	v_pk_mul_f32 v[112:113], v[112:113], v[32:33]
	v_pk_mul_f32 v[114:115], v[114:115], v[34:35]
	v_pk_fma_f32 v[100:101], v[100:101], v[164:165], v[148:149]
	v_pk_fma_f32 v[102:103], v[102:103], v[166:167], v[150:151]
	v_pk_fma_f32 v[104:105], v[104:105], v[168:169], v[152:153]
	v_pk_fma_f32 v[106:107], v[106:107], v[170:171], v[154:155]
	v_pk_fma_f32 v[108:109], v[108:109], v[172:173], v[156:157]
	v_pk_fma_f32 v[110:111], v[110:111], v[174:175], v[158:159]
	v_pk_fma_f32 v[112:113], v[112:113], v[176:177], v[160:161]
	v_pk_fma_f32 v[114:115], v[114:115], v[178:179], v[162:163]
	v_cvt_pk_bf16_f32 v232, v100, v101
	v_cvt_pk_bf16_f32 v233, v102, v103
	v_cvt_pk_bf16_f32 v234, v104, v105
	v_cvt_pk_bf16_f32 v235, v106, v107
	v_cvt_pk_bf16_f32 v236, v108, v109
	v_cvt_pk_bf16_f32 v237, v110, v111
	v_cvt_pk_bf16_f32 v238, v112, v113
	v_cvt_pk_bf16_f32 v239, v114, v115
	global_store_dwordx2 v1, v[232:233], s[10:11]
	global_store_dwordx2 v1, v[234:235], s[10:11] offset:512
	global_store_dwordx2 v1, v[236:237], s[10:11] offset:1024
	global_store_dwordx2 v1, v[238:239], s[10:11] offset:1536
	s_add_u32 s10, s10, 0x400000
	s_addc_u32 s11, s11, 0
	global_load_dwordx4 v[100:103], v0, s[8:9]
	global_load_dwordx4 v[104:107], v0, s[8:9] offset:1024
	global_load_dwordx4 v[108:111], v0, s[8:9] offset:2048
	global_load_dwordx4 v[112:115], v0, s[8:9] offset:3072
	s_add_u32 s8, s8, 0x800000
	s_addc_u32 s9, s9, 0
	s_waitcnt vmcnt(32)
	v_pk_mul_f32 v[4:5], v[116:117], v[116:117]
	v_pk_fma_f32 v[4:5], v[118:119], v[118:119], v[4:5]
	v_pk_fma_f32 v[4:5], v[120:121], v[120:121], v[4:5]
	v_pk_fma_f32 v[4:5], v[122:123], v[122:123], v[4:5]
	v_pk_fma_f32 v[4:5], v[124:125], v[124:125], v[4:5]
	v_pk_fma_f32 v[4:5], v[126:127], v[126:127], v[4:5]
	v_pk_fma_f32 v[4:5], v[128:129], v[128:129], v[4:5]
	v_pk_fma_f32 v[4:5], v[130:131], v[130:131], v[4:5]
	v_add_f32_e32 v4, v4, v5
	s_nop 1
	v_add_f32_dpp v4, v4, v4 quad_perm:[1,0,3,2] row_mask:0xf bank_mask:0xf
	s_nop 1
	v_add_f32_dpp v4, v4, v4 quad_perm:[2,3,0,1] row_mask:0xf bank_mask:0xf
	s_nop 1
	v_add_f32_dpp v4, v4, v4 row_half_mirror row_mask:0xf bank_mask:0xf
	s_nop 1
	v_add_f32_dpp v4, v4, v4 row_mirror row_mask:0xf bank_mask:0xf
	s_nop 1
	v_add_f32_dpp v4, v4, v4 row_bcast:15 row_mask:0xa bank_mask:0xf
	s_nop 1
	v_add_f32_dpp v4, v4, v4 row_bcast:31 row_mask:0xc bank_mask:0xf
	s_nop 1
	v_readlane_b32 s20, v4, 63
	s_nop 1
	v_fma_f32 v6, s20, v16, v17
	v_rsq_f32_e32 v6, v6
	s_nop 0
	v_pk_mul_f32 v[116:117], v[116:117], v[6:7] op_sel_hi:[1,0]
	v_pk_mul_f32 v[118:119], v[118:119], v[6:7] op_sel_hi:[1,0]
	v_pk_mul_f32 v[120:121], v[120:121], v[6:7] op_sel_hi:[1,0]
	v_pk_mul_f32 v[122:123], v[122:123], v[6:7] op_sel_hi:[1,0]
	v_pk_mul_f32 v[124:125], v[124:125], v[6:7] op_sel_hi:[1,0]
	v_pk_mul_f32 v[126:127], v[126:127], v[6:7] op_sel_hi:[1,0]
	v_pk_mul_f32 v[128:129], v[128:129], v[6:7] op_sel_hi:[1,0]
	v_pk_mul_f32 v[130:131], v[130:131], v[6:7] op_sel_hi:[1,0]
	v_pk_mul_f32 v[116:117], v[116:117], v[20:21]
	v_pk_mul_f32 v[118:119], v[118:119], v[22:23]
	v_pk_mul_f32 v[120:121], v[120:121], v[24:25]
	v_pk_mul_f32 v[122:123], v[122:123], v[26:27]
	v_pk_mul_f32 v[124:125], v[124:125], v[28:29]
	v_pk_mul_f32 v[126:127], v[126:127], v[30:31]
	v_pk_mul_f32 v[128:129], v[128:129], v[32:33]
	v_pk_mul_f32 v[130:131], v[130:131], v[34:35]
	v_pk_fma_f32 v[116:117], v[116:117], v[164:165], v[148:149]
	v_pk_fma_f32 v[118:119], v[118:119], v[166:167], v[150:151]
	v_pk_fma_f32 v[120:121], v[120:121], v[168:169], v[152:153]
	v_pk_fma_f32 v[122:123], v[122:123], v[170:171], v[154:155]
	v_pk_fma_f32 v[124:125], v[124:125], v[172:173], v[156:157]
	v_pk_fma_f32 v[126:127], v[126:127], v[174:175], v[158:159]
	v_pk_fma_f32 v[128:129], v[128:129], v[176:177], v[160:161]
	v_pk_fma_f32 v[130:131], v[130:131], v[178:179], v[162:163]
	v_cvt_pk_bf16_f32 v240, v116, v117
	v_cvt_pk_bf16_f32 v241, v118, v119
	v_cvt_pk_bf16_f32 v242, v120, v121
	v_cvt_pk_bf16_f32 v243, v122, v123
	v_cvt_pk_bf16_f32 v244, v124, v125
	v_cvt_pk_bf16_f32 v245, v126, v127
	v_cvt_pk_bf16_f32 v246, v128, v129
	v_cvt_pk_bf16_f32 v247, v130, v131
	global_store_dwordx2 v1, v[240:241], s[10:11]
	global_store_dwordx2 v1, v[242:243], s[10:11] offset:512
	global_store_dwordx2 v1, v[244:245], s[10:11] offset:1024
	global_store_dwordx2 v1, v[246:247], s[10:11] offset:1536
	s_add_u32 s10, s10, 0x400000
	s_addc_u32 s11, s11, 0
	global_load_dwordx4 v[116:119], v0, s[8:9]
	global_load_dwordx4 v[120:123], v0, s[8:9] offset:1024
	global_load_dwordx4 v[124:127], v0, s[8:9] offset:2048
	global_load_dwordx4 v[128:131], v0, s[8:9] offset:3072
	s_add_u32 s8, s8, 0x800000
	s_addc_u32 s9, s9, 0
	s_waitcnt vmcnt(24)
	v_pk_add_f32 v[52:53], v[52:53], v[18:19]
	v_pk_add_f32 v[54:55], v[54:55], v[18:19]
	v_pk_add_f32 v[56:57], v[56:57], v[18:19]
	v_pk_add_f32 v[58:59], v[58:59], v[18:19]
	v_pk_add_f32 v[60:61], v[60:61], v[18:19]
	v_pk_add_f32 v[62:63], v[62:63], v[18:19]
	v_pk_add_f32 v[64:65], v[64:65], v[18:19]
	v_pk_add_f32 v[66:67], v[66:67], v[18:19]
	s_add_u32 s14, s12, 0x12000
	s_addc_u32 s15, s13, 0
	s_add_u32 s16, s14, 0x1000
	s_addc_u32 s17, s15, 0
	global_load_dwordx4 v[148:151], v0, s[14:15]
	global_load_dwordx4 v[152:155], v0, s[14:15] offset:1024
	global_load_dwordx4 v[156:159], v0, s[14:15] offset:2048
	global_load_dwordx4 v[160:163], v0, s[14:15] offset:3072
	global_load_dwordx4 v[164:167], v0, s[16:17]
	global_load_dwordx4 v[168:171], v0, s[16:17] offset:1024
	global_load_dwordx4 v[172:175], v0, s[16:17] offset:2048
	global_load_dwordx4 v[176:179], v0, s[16:17] offset:3072
	v_pk_mul_f32 v[4:5], v[68:69], v[68:69]
	v_pk_fma_f32 v[4:5], v[70:71], v[70:71], v[4:5]
	v_pk_fma_f32 v[4:5], v[72:73], v[72:73], v[4:5]
	v_pk_fma_f32 v[4:5], v[74:75], v[74:75], v[4:5]
	v_pk_fma_f32 v[4:5], v[76:77], v[76:77], v[4:5]
	v_pk_fma_f32 v[4:5], v[78:79], v[78:79], v[4:5]
	v_pk_fma_f32 v[4:5], v[80:81], v[80:81], v[4:5]
	v_pk_fma_f32 v[4:5], v[82:83], v[82:83], v[4:5]
	v_add_f32_e32 v4, v4, v5
	s_nop 1
	v_add_f32_dpp v4, v4, v4 quad_perm:[1,0,3,2] row_mask:0xf bank_mask:0xf
	s_nop 1
	v_add_f32_dpp v4, v4, v4 quad_perm:[2,3,0,1] row_mask:0xf bank_mask:0xf
	s_nop 1
	v_add_f32_dpp v4, v4, v4 row_half_mirror row_mask:0xf bank_mask:0xf
	s_nop 1
	v_add_f32_dpp v4, v4, v4 row_mirror row_mask:0xf bank_mask:0xf
	s_nop 1
	v_add_f32_dpp v4, v4, v4 row_bcast:15 row_mask:0xa bank_mask:0xf
	s_nop 1
	v_add_f32_dpp v4, v4, v4 row_bcast:31 row_mask:0xc bank_mask:0xf
	s_nop 1
	v_readlane_b32 s20, v4, 63
	s_nop 1
	v_fma_f32 v6, s20, v16, v17
	v_rsq_f32_e32 v6, v6
	s_nop 0
	v_pk_mul_f32 v[68:69], v[68:69], v[6:7] op_sel_hi:[1,0]
	v_pk_mul_f32 v[70:71], v[70:71], v[6:7] op_sel_hi:[1,0]
	v_pk_mul_f32 v[72:73], v[72:73], v[6:7] op_sel_hi:[1,0]
	v_pk_mul_f32 v[74:75], v[74:75], v[6:7] op_sel_hi:[1,0]
	v_pk_mul_f32 v[76:77], v[76:77], v[6:7] op_sel_hi:[1,0]
	v_pk_mul_f32 v[78:79], v[78:79], v[6:7] op_sel_hi:[1,0]
	v_pk_mul_f32 v[80:81], v[80:81], v[6:7] op_sel_hi:[1,0]
	v_pk_mul_f32 v[82:83], v[82:83], v[6:7] op_sel_hi:[1,0]
	v_pk_mul_f32 v[68:69], v[68:69], v[20:21]
	v_pk_mul_f32 v[70:71], v[70:71], v[22:23]
	v_pk_mul_f32 v[72:73], v[72:73], v[24:25]
	v_pk_mul_f32 v[74:75], v[74:75], v[26:27]
	v_pk_mul_f32 v[76:77], v[76:77], v[28:29]
	v_pk_mul_f32 v[78:79], v[78:79], v[30:31]
	v_pk_mul_f32 v[80:81], v[80:81], v[32:33]
	v_pk_mul_f32 v[82:83], v[82:83], v[34:35]
	v_pk_fma_f32 v[68:69], v[68:69], v[52:53], v[36:37]
	v_pk_fma_f32 v[70:71], v[70:71], v[54:55], v[38:39]
	v_pk_fma_f32 v[72:73], v[72:73], v[56:57], v[40:41]
	v_pk_fma_f32 v[74:75], v[74:75], v[58:59], v[42:43]
	v_pk_fma_f32 v[76:77], v[76:77], v[60:61], v[44:45]
	v_pk_fma_f32 v[78:79], v[78:79], v[62:63], v[46:47]
	v_pk_fma_f32 v[80:81], v[80:81], v[64:65], v[48:49]
	v_pk_fma_f32 v[82:83], v[82:83], v[66:67], v[50:51]
	v_cvt_pk_bf16_f32 v232, v68, v69
	v_cvt_pk_bf16_f32 v233, v70, v71
	v_cvt_pk_bf16_f32 v234, v72, v73
	v_cvt_pk_bf16_f32 v235, v74, v75
	v_cvt_pk_bf16_f32 v236, v76, v77
	v_cvt_pk_bf16_f32 v237, v78, v79
	v_cvt_pk_bf16_f32 v238, v80, v81
	v_cvt_pk_bf16_f32 v239, v82, v83
	global_store_dwordx2 v1, v[232:233], s[10:11]
	global_store_dwordx2 v1, v[234:235], s[10:11] offset:512
	global_store_dwordx2 v1, v[236:237], s[10:11] offset:1024
	global_store_dwordx2 v1, v[238:239], s[10:11] offset:1536
	s_add_u32 s10, s10, 0x400000
	s_addc_u32 s11, s11, 0
	global_load_dwordx4 v[68:71], v0, s[8:9]
	global_load_dwordx4 v[72:75], v0, s[8:9] offset:1024
	global_load_dwordx4 v[76:79], v0, s[8:9] offset:2048
	global_load_dwordx4 v[80:83], v0, s[8:9] offset:3072
	s_add_u32 s8, s8, 0x800000
	s_addc_u32 s9, s9, 0
	s_waitcnt vmcnt(32)
	v_pk_mul_f32 v[4:5], v[84:85], v[84:85]
	v_pk_fma_f32 v[4:5], v[86:87], v[86:87], v[4:5]
	v_pk_fma_f32 v[4:5], v[88:89], v[88:89], v[4:5]
	v_pk_fma_f32 v[4:5], v[90:91], v[90:91], v[4:5]
	v_pk_fma_f32 v[4:5], v[92:93], v[92:93], v[4:5]
	v_pk_fma_f32 v[4:5], v[94:95], v[94:95], v[4:5]
	v_pk_fma_f32 v[4:5], v[96:97], v[96:97], v[4:5]
	v_pk_fma_f32 v[4:5], v[98:99], v[98:99], v[4:5]
	v_add_f32_e32 v4, v4, v5
	s_nop 1
	v_add_f32_dpp v4, v4, v4 quad_perm:[1,0,3,2] row_mask:0xf bank_mask:0xf
	s_nop 1
	v_add_f32_dpp v4, v4, v4 quad_perm:[2,3,0,1] row_mask:0xf bank_mask:0xf
	s_nop 1
	v_add_f32_dpp v4, v4, v4 row_half_mirror row_mask:0xf bank_mask:0xf
	s_nop 1
	v_add_f32_dpp v4, v4, v4 row_mirror row_mask:0xf bank_mask:0xf
	s_nop 1
	v_add_f32_dpp v4, v4, v4 row_bcast:15 row_mask:0xa bank_mask:0xf
	s_nop 1
	v_add_f32_dpp v4, v4, v4 row_bcast:31 row_mask:0xc bank_mask:0xf
	s_nop 1
	v_readlane_b32 s20, v4, 63
	s_nop 1
	v_fma_f32 v6, s20, v16, v17
	v_rsq_f32_e32 v6, v6
	s_nop 0
	v_pk_mul_f32 v[84:85], v[84:85], v[6:7] op_sel_hi:[1,0]
	v_pk_mul_f32 v[86:87], v[86:87], v[6:7] op_sel_hi:[1,0]
	v_pk_mul_f32 v[88:89], v[88:89], v[6:7] op_sel_hi:[1,0]
	v_pk_mul_f32 v[90:91], v[90:91], v[6:7] op_sel_hi:[1,0]
	v_pk_mul_f32 v[92:93], v[92:93], v[6:7] op_sel_hi:[1,0]
	v_pk_mul_f32 v[94:95], v[94:95], v[6:7] op_sel_hi:[1,0]
	v_pk_mul_f32 v[96:97], v[96:97], v[6:7] op_sel_hi:[1,0]
	v_pk_mul_f32 v[98:99], v[98:99], v[6:7] op_sel_hi:[1,0]
	v_pk_mul_f32 v[84:85], v[84:85], v[20:21]
	v_pk_mul_f32 v[86:87], v[86:87], v[22:23]
	v_pk_mul_f32 v[88:89], v[88:89], v[24:25]
	v_pk_mul_f32 v[90:91], v[90:91], v[26:27]
	v_pk_mul_f32 v[92:93], v[92:93], v[28:29]
	v_pk_mul_f32 v[94:95], v[94:95], v[30:31]
	v_pk_mul_f32 v[96:97], v[96:97], v[32:33]
	v_pk_mul_f32 v[98:99], v[98:99], v[34:35]
	v_pk_fma_f32 v[84:85], v[84:85], v[52:53], v[36:37]
	v_pk_fma_f32 v[86:87], v[86:87], v[54:55], v[38:39]
	v_pk_fma_f32 v[88:89], v[88:89], v[56:57], v[40:41]
	v_pk_fma_f32 v[90:91], v[90:91], v[58:59], v[42:43]
	v_pk_fma_f32 v[92:93], v[92:93], v[60:61], v[44:45]
	v_pk_fma_f32 v[94:95], v[94:95], v[62:63], v[46:47]
	v_pk_fma_f32 v[96:97], v[96:97], v[64:65], v[48:49]
	v_pk_fma_f32 v[98:99], v[98:99], v[66:67], v[50:51]
	v_cvt_pk_bf16_f32 v240, v84, v85
	v_cvt_pk_bf16_f32 v241, v86, v87
	v_cvt_pk_bf16_f32 v242, v88, v89
	v_cvt_pk_bf16_f32 v243, v90, v91
	v_cvt_pk_bf16_f32 v244, v92, v93
	v_cvt_pk_bf16_f32 v245, v94, v95
	v_cvt_pk_bf16_f32 v246, v96, v97
	v_cvt_pk_bf16_f32 v247, v98, v99
	global_store_dwordx2 v1, v[240:241], s[10:11]
	global_store_dwordx2 v1, v[242:243], s[10:11] offset:512
	global_store_dwordx2 v1, v[244:245], s[10:11] offset:1024
	global_store_dwordx2 v1, v[246:247], s[10:11] offset:1536
	s_add_u32 s10, s10, 0x400000
	s_addc_u32 s11, s11, 0
	global_load_dwordx4 v[84:87], v0, s[8:9]
	global_load_dwordx4 v[88:91], v0, s[8:9] offset:1024
	global_load_dwordx4 v[92:95], v0, s[8:9] offset:2048
	global_load_dwordx4 v[96:99], v0, s[8:9] offset:3072
	s_add_u32 s8, s8, 0x800000
	s_addc_u32 s9, s9, 0
	s_waitcnt vmcnt(32)
	v_pk_mul_f32 v[4:5], v[100:101], v[100:101]
	v_pk_fma_f32 v[4:5], v[102:103], v[102:103], v[4:5]
	v_pk_fma_f32 v[4:5], v[104:105], v[104:105], v[4:5]
	v_pk_fma_f32 v[4:5], v[106:107], v[106:107], v[4:5]
	v_pk_fma_f32 v[4:5], v[108:109], v[108:109], v[4:5]
	v_pk_fma_f32 v[4:5], v[110:111], v[110:111], v[4:5]
	v_pk_fma_f32 v[4:5], v[112:113], v[112:113], v[4:5]
	v_pk_fma_f32 v[4:5], v[114:115], v[114:115], v[4:5]
	v_add_f32_e32 v4, v4, v5
	s_nop 1
	v_add_f32_dpp v4, v4, v4 quad_perm:[1,0,3,2] row_mask:0xf bank_mask:0xf
	s_nop 1
	v_add_f32_dpp v4, v4, v4 quad_perm:[2,3,0,1] row_mask:0xf bank_mask:0xf
	s_nop 1
	v_add_f32_dpp v4, v4, v4 row_half_mirror row_mask:0xf bank_mask:0xf
	s_nop 1
	v_add_f32_dpp v4, v4, v4 row_mirror row_mask:0xf bank_mask:0xf
	s_nop 1
	v_add_f32_dpp v4, v4, v4 row_bcast:15 row_mask:0xa bank_mask:0xf
	s_nop 1
	v_add_f32_dpp v4, v4, v4 row_bcast:31 row_mask:0xc bank_mask:0xf
	s_nop 1
	v_readlane_b32 s20, v4, 63
	s_nop 1
	v_fma_f32 v6, s20, v16, v17
	v_rsq_f32_e32 v6, v6
	s_nop 0
	v_pk_mul_f32 v[100:101], v[100:101], v[6:7] op_sel_hi:[1,0]
	v_pk_mul_f32 v[102:103], v[102:103], v[6:7] op_sel_hi:[1,0]
	v_pk_mul_f32 v[104:105], v[104:105], v[6:7] op_sel_hi:[1,0]
	v_pk_mul_f32 v[106:107], v[106:107], v[6:7] op_sel_hi:[1,0]
	v_pk_mul_f32 v[108:109], v[108:109], v[6:7] op_sel_hi:[1,0]
	v_pk_mul_f32 v[110:111], v[110:111], v[6:7] op_sel_hi:[1,0]
	v_pk_mul_f32 v[112:113], v[112:113], v[6:7] op_sel_hi:[1,0]
	v_pk_mul_f32 v[114:115], v[114:115], v[6:7] op_sel_hi:[1,0]
	v_pk_mul_f32 v[100:101], v[100:101], v[20:21]
	v_pk_mul_f32 v[102:103], v[102:103], v[22:23]
	v_pk_mul_f32 v[104:105], v[104:105], v[24:25]
	v_pk_mul_f32 v[106:107], v[106:107], v[26:27]
	v_pk_mul_f32 v[108:109], v[108:109], v[28:29]
	v_pk_mul_f32 v[110:111], v[110:111], v[30:31]
	v_pk_mul_f32 v[112:113], v[112:113], v[32:33]
	v_pk_mul_f32 v[114:115], v[114:115], v[34:35]
	v_pk_fma_f32 v[100:101], v[100:101], v[52:53], v[36:37]
	v_pk_fma_f32 v[102:103], v[102:103], v[54:55], v[38:39]
	v_pk_fma_f32 v[104:105], v[104:105], v[56:57], v[40:41]
	v_pk_fma_f32 v[106:107], v[106:107], v[58:59], v[42:43]
	v_pk_fma_f32 v[108:109], v[108:109], v[60:61], v[44:45]
	v_pk_fma_f32 v[110:111], v[110:111], v[62:63], v[46:47]
	v_pk_fma_f32 v[112:113], v[112:113], v[64:65], v[48:49]
	v_pk_fma_f32 v[114:115], v[114:115], v[66:67], v[50:51]
	v_cvt_pk_bf16_f32 v232, v100, v101
	v_cvt_pk_bf16_f32 v233, v102, v103
	v_cvt_pk_bf16_f32 v234, v104, v105
	v_cvt_pk_bf16_f32 v235, v106, v107
	v_cvt_pk_bf16_f32 v236, v108, v109
	v_cvt_pk_bf16_f32 v237, v110, v111
	v_cvt_pk_bf16_f32 v238, v112, v113
	v_cvt_pk_bf16_f32 v239, v114, v115
	global_store_dwordx2 v1, v[232:233], s[10:11]
	global_store_dwordx2 v1, v[234:235], s[10:11] offset:512
	global_store_dwordx2 v1, v[236:237], s[10:11] offset:1024
	global_store_dwordx2 v1, v[238:239], s[10:11] offset:1536
	s_add_u32 s10, s10, 0x400000
	s_addc_u32 s11, s11, 0
	global_load_dwordx4 v[100:103], v0, s[8:9]
	global_load_dwordx4 v[104:107], v0, s[8:9] offset:1024
	global_load_dwordx4 v[108:111], v0, s[8:9] offset:2048
	global_load_dwordx4 v[112:115], v0, s[8:9] offset:3072
	s_add_u32 s8, s8, 0x800000
	s_addc_u32 s9, s9, 0
	s_waitcnt vmcnt(32)
	v_pk_mul_f32 v[4:5], v[116:117], v[116:117]
	v_pk_fma_f32 v[4:5], v[118:119], v[118:119], v[4:5]
	v_pk_fma_f32 v[4:5], v[120:121], v[120:121], v[4:5]
	v_pk_fma_f32 v[4:5], v[122:123], v[122:123], v[4:5]
	v_pk_fma_f32 v[4:5], v[124:125], v[124:125], v[4:5]
	v_pk_fma_f32 v[4:5], v[126:127], v[126:127], v[4:5]
	v_pk_fma_f32 v[4:5], v[128:129], v[128:129], v[4:5]
	v_pk_fma_f32 v[4:5], v[130:131], v[130:131], v[4:5]
	v_add_f32_e32 v4, v4, v5
	s_nop 1
	v_add_f32_dpp v4, v4, v4 quad_perm:[1,0,3,2] row_mask:0xf bank_mask:0xf
	s_nop 1
	v_add_f32_dpp v4, v4, v4 quad_perm:[2,3,0,1] row_mask:0xf bank_mask:0xf
	s_nop 1
	v_add_f32_dpp v4, v4, v4 row_half_mirror row_mask:0xf bank_mask:0xf
	s_nop 1
	v_add_f32_dpp v4, v4, v4 row_mirror row_mask:0xf bank_mask:0xf
	s_nop 1
	v_add_f32_dpp v4, v4, v4 row_bcast:15 row_mask:0xa bank_mask:0xf
	s_nop 1
	v_add_f32_dpp v4, v4, v4 row_bcast:31 row_mask:0xc bank_mask:0xf
	s_nop 1
	v_readlane_b32 s20, v4, 63
	s_nop 1
	v_fma_f32 v6, s20, v16, v17
	v_rsq_f32_e32 v6, v6
	s_nop 0
	v_pk_mul_f32 v[116:117], v[116:117], v[6:7] op_sel_hi:[1,0]
	v_pk_mul_f32 v[118:119], v[118:119], v[6:7] op_sel_hi:[1,0]
	v_pk_mul_f32 v[120:121], v[120:121], v[6:7] op_sel_hi:[1,0]
	v_pk_mul_f32 v[122:123], v[122:123], v[6:7] op_sel_hi:[1,0]
	v_pk_mul_f32 v[124:125], v[124:125], v[6:7] op_sel_hi:[1,0]
	v_pk_mul_f32 v[126:127], v[126:127], v[6:7] op_sel_hi:[1,0]
	v_pk_mul_f32 v[128:129], v[128:129], v[6:7] op_sel_hi:[1,0]
	v_pk_mul_f32 v[130:131], v[130:131], v[6:7] op_sel_hi:[1,0]
	v_pk_mul_f32 v[116:117], v[116:117], v[20:21]
	v_pk_mul_f32 v[118:119], v[118:119], v[22:23]
	v_pk_mul_f32 v[120:121], v[120:121], v[24:25]
	v_pk_mul_f32 v[122:123], v[122:123], v[26:27]
	v_pk_mul_f32 v[124:125], v[124:125], v[28:29]
	v_pk_mul_f32 v[126:127], v[126:127], v[30:31]
	v_pk_mul_f32 v[128:129], v[128:129], v[32:33]
	v_pk_mul_f32 v[130:131], v[130:131], v[34:35]
	v_pk_fma_f32 v[116:117], v[116:117], v[52:53], v[36:37]
	v_pk_fma_f32 v[118:119], v[118:119], v[54:55], v[38:39]
	v_pk_fma_f32 v[120:121], v[120:121], v[56:57], v[40:41]
	v_pk_fma_f32 v[122:123], v[122:123], v[58:59], v[42:43]
	v_pk_fma_f32 v[124:125], v[124:125], v[60:61], v[44:45]
	v_pk_fma_f32 v[126:127], v[126:127], v[62:63], v[46:47]
	v_pk_fma_f32 v[128:129], v[128:129], v[64:65], v[48:49]
	v_pk_fma_f32 v[130:131], v[130:131], v[66:67], v[50:51]
	v_cvt_pk_bf16_f32 v240, v116, v117
	v_cvt_pk_bf16_f32 v241, v118, v119
	v_cvt_pk_bf16_f32 v242, v120, v121
	v_cvt_pk_bf16_f32 v243, v122, v123
	v_cvt_pk_bf16_f32 v244, v124, v125
	v_cvt_pk_bf16_f32 v245, v126, v127
	v_cvt_pk_bf16_f32 v246, v128, v129
	v_cvt_pk_bf16_f32 v247, v130, v131
	global_store_dwordx2 v1, v[240:241], s[10:11]
	global_store_dwordx2 v1, v[242:243], s[10:11] offset:512
	global_store_dwordx2 v1, v[244:245], s[10:11] offset:1024
	global_store_dwordx2 v1, v[246:247], s[10:11] offset:1536
	s_add_u32 s10, s10, 0x400000
	s_addc_u32 s11, s11, 0
	global_load_dwordx4 v[116:119], v0, s[8:9]
	global_load_dwordx4 v[120:123], v0, s[8:9] offset:1024
	global_load_dwordx4 v[124:127], v0, s[8:9] offset:2048
	global_load_dwordx4 v[128:131], v0, s[8:9] offset:3072
	s_add_u32 s8, s8, 0x800000
	s_addc_u32 s9, s9, 0
	s_waitcnt vmcnt(24)
	v_pk_add_f32 v[164:165], v[164:165], v[18:19]
	v_pk_add_f32 v[166:167], v[166:167], v[18:19]
	v_pk_add_f32 v[168:169], v[168:169], v[18:19]
	v_pk_add_f32 v[170:171], v[170:171], v[18:19]
	v_pk_add_f32 v[172:173], v[172:173], v[18:19]
	v_pk_add_f32 v[174:175], v[174:175], v[18:19]
	v_pk_add_f32 v[176:177], v[176:177], v[18:19]
	v_pk_add_f32 v[178:179], v[178:179], v[18:19]
	s_add_u32 s14, s12, 0x18000
	s_addc_u32 s15, s13, 0
	s_add_u32 s16, s14, 0x1000
	s_addc_u32 s17, s15, 0
	global_load_dwordx4 v[36:39], v0, s[14:15]
	global_load_dwordx4 v[40:43], v0, s[14:15] offset:1024
	global_load_dwordx4 v[44:47], v0, s[14:15] offset:2048
	global_load_dwordx4 v[48:51], v0, s[14:15] offset:3072
	global_load_dwordx4 v[52:55], v0, s[16:17]
	global_load_dwordx4 v[56:59], v0, s[16:17] offset:1024
	global_load_dwordx4 v[60:63], v0, s[16:17] offset:2048
	global_load_dwordx4 v[64:67], v0, s[16:17] offset:3072
	v_pk_mul_f32 v[4:5], v[68:69], v[68:69]
	v_pk_fma_f32 v[4:5], v[70:71], v[70:71], v[4:5]
	v_pk_fma_f32 v[4:5], v[72:73], v[72:73], v[4:5]
	v_pk_fma_f32 v[4:5], v[74:75], v[74:75], v[4:5]
	v_pk_fma_f32 v[4:5], v[76:77], v[76:77], v[4:5]
	v_pk_fma_f32 v[4:5], v[78:79], v[78:79], v[4:5]
	v_pk_fma_f32 v[4:5], v[80:81], v[80:81], v[4:5]
	v_pk_fma_f32 v[4:5], v[82:83], v[82:83], v[4:5]
	v_add_f32_e32 v4, v4, v5
	s_nop 1
	v_add_f32_dpp v4, v4, v4 quad_perm:[1,0,3,2] row_mask:0xf bank_mask:0xf
	s_nop 1
	v_add_f32_dpp v4, v4, v4 quad_perm:[2,3,0,1] row_mask:0xf bank_mask:0xf
	s_nop 1
	v_add_f32_dpp v4, v4, v4 row_half_mirror row_mask:0xf bank_mask:0xf
	s_nop 1
	v_add_f32_dpp v4, v4, v4 row_mirror row_mask:0xf bank_mask:0xf
	s_nop 1
	v_add_f32_dpp v4, v4, v4 row_bcast:15 row_mask:0xa bank_mask:0xf
	s_nop 1
	v_add_f32_dpp v4, v4, v4 row_bcast:31 row_mask:0xc bank_mask:0xf
	s_nop 1
	v_readlane_b32 s20, v4, 63
	s_nop 1
	v_fma_f32 v6, s20, v16, v17
	v_rsq_f32_e32 v6, v6
	s_nop 0
	v_pk_mul_f32 v[68:69], v[68:69], v[6:7] op_sel_hi:[1,0]
	v_pk_mul_f32 v[70:71], v[70:71], v[6:7] op_sel_hi:[1,0]
	v_pk_mul_f32 v[72:73], v[72:73], v[6:7] op_sel_hi:[1,0]
	v_pk_mul_f32 v[74:75], v[74:75], v[6:7] op_sel_hi:[1,0]
	v_pk_mul_f32 v[76:77], v[76:77], v[6:7] op_sel_hi:[1,0]
	v_pk_mul_f32 v[78:79], v[78:79], v[6:7] op_sel_hi:[1,0]
	v_pk_mul_f32 v[80:81], v[80:81], v[6:7] op_sel_hi:[1,0]
	v_pk_mul_f32 v[82:83], v[82:83], v[6:7] op_sel_hi:[1,0]
	v_pk_mul_f32 v[68:69], v[68:69], v[20:21]
	v_pk_mul_f32 v[70:71], v[70:71], v[22:23]
	v_pk_mul_f32 v[72:73], v[72:73], v[24:25]
	v_pk_mul_f32 v[74:75], v[74:75], v[26:27]
	v_pk_mul_f32 v[76:77], v[76:77], v[28:29]
	v_pk_mul_f32 v[78:79], v[78:79], v[30:31]
	v_pk_mul_f32 v[80:81], v[80:81], v[32:33]
	v_pk_mul_f32 v[82:83], v[82:83], v[34:35]
	v_pk_fma_f32 v[68:69], v[68:69], v[164:165], v[148:149]
	v_pk_fma_f32 v[70:71], v[70:71], v[166:167], v[150:151]
	v_pk_fma_f32 v[72:73], v[72:73], v[168:169], v[152:153]
	v_pk_fma_f32 v[74:75], v[74:75], v[170:171], v[154:155]
	v_pk_fma_f32 v[76:77], v[76:77], v[172:173], v[156:157]
	v_pk_fma_f32 v[78:79], v[78:79], v[174:175], v[158:159]
	v_pk_fma_f32 v[80:81], v[80:81], v[176:177], v[160:161]
	v_pk_fma_f32 v[82:83], v[82:83], v[178:179], v[162:163]
	v_cvt_pk_bf16_f32 v232, v68, v69
	v_cvt_pk_bf16_f32 v233, v70, v71
	v_cvt_pk_bf16_f32 v234, v72, v73
	v_cvt_pk_bf16_f32 v235, v74, v75
	v_cvt_pk_bf16_f32 v236, v76, v77
	v_cvt_pk_bf16_f32 v237, v78, v79
	v_cvt_pk_bf16_f32 v238, v80, v81
	v_cvt_pk_bf16_f32 v239, v82, v83
	global_store_dwordx2 v1, v[232:233], s[10:11]
	global_store_dwordx2 v1, v[234:235], s[10:11] offset:512
	global_store_dwordx2 v1, v[236:237], s[10:11] offset:1024
	global_store_dwordx2 v1, v[238:239], s[10:11] offset:1536
	s_add_u32 s10, s10, 0x400000
	s_addc_u32 s11, s11, 0
	s_waitcnt vmcnt(28)
	v_pk_mul_f32 v[4:5], v[84:85], v[84:85]
	v_pk_fma_f32 v[4:5], v[86:87], v[86:87], v[4:5]
	v_pk_fma_f32 v[4:5], v[88:89], v[88:89], v[4:5]
	v_pk_fma_f32 v[4:5], v[90:91], v[90:91], v[4:5]
	v_pk_fma_f32 v[4:5], v[92:93], v[92:93], v[4:5]
	v_pk_fma_f32 v[4:5], v[94:95], v[94:95], v[4:5]
	v_pk_fma_f32 v[4:5], v[96:97], v[96:97], v[4:5]
	v_pk_fma_f32 v[4:5], v[98:99], v[98:99], v[4:5]
	v_add_f32_e32 v4, v4, v5
	s_nop 1
	v_add_f32_dpp v4, v4, v4 quad_perm:[1,0,3,2] row_mask:0xf bank_mask:0xf
	s_nop 1
	v_add_f32_dpp v4, v4, v4 quad_perm:[2,3,0,1] row_mask:0xf bank_mask:0xf
	s_nop 1
	v_add_f32_dpp v4, v4, v4 row_half_mirror row_mask:0xf bank_mask:0xf
	s_nop 1
	v_add_f32_dpp v4, v4, v4 row_mirror row_mask:0xf bank_mask:0xf
	s_nop 1
	v_add_f32_dpp v4, v4, v4 row_bcast:15 row_mask:0xa bank_mask:0xf
	s_nop 1
	v_add_f32_dpp v4, v4, v4 row_bcast:31 row_mask:0xc bank_mask:0xf
	s_nop 1
	v_readlane_b32 s20, v4, 63
	s_nop 1
	v_fma_f32 v6, s20, v16, v17
	v_rsq_f32_e32 v6, v6
	s_nop 0
	v_pk_mul_f32 v[84:85], v[84:85], v[6:7] op_sel_hi:[1,0]
	v_pk_mul_f32 v[86:87], v[86:87], v[6:7] op_sel_hi:[1,0]
	v_pk_mul_f32 v[88:89], v[88:89], v[6:7] op_sel_hi:[1,0]
	v_pk_mul_f32 v[90:91], v[90:91], v[6:7] op_sel_hi:[1,0]
	v_pk_mul_f32 v[92:93], v[92:93], v[6:7] op_sel_hi:[1,0]
	v_pk_mul_f32 v[94:95], v[94:95], v[6:7] op_sel_hi:[1,0]
	v_pk_mul_f32 v[96:97], v[96:97], v[6:7] op_sel_hi:[1,0]
	v_pk_mul_f32 v[98:99], v[98:99], v[6:7] op_sel_hi:[1,0]
	v_pk_mul_f32 v[84:85], v[84:85], v[20:21]
	v_pk_mul_f32 v[86:87], v[86:87], v[22:23]
	v_pk_mul_f32 v[88:89], v[88:89], v[24:25]
	v_pk_mul_f32 v[90:91], v[90:91], v[26:27]
	v_pk_mul_f32 v[92:93], v[92:93], v[28:29]
	v_pk_mul_f32 v[94:95], v[94:95], v[30:31]
	v_pk_mul_f32 v[96:97], v[96:97], v[32:33]
	v_pk_mul_f32 v[98:99], v[98:99], v[34:35]
	v_pk_fma_f32 v[84:85], v[84:85], v[164:165], v[148:149]
	v_pk_fma_f32 v[86:87], v[86:87], v[166:167], v[150:151]
	v_pk_fma_f32 v[88:89], v[88:89], v[168:169], v[152:153]
	v_pk_fma_f32 v[90:91], v[90:91], v[170:171], v[154:155]
	v_pk_fma_f32 v[92:93], v[92:93], v[172:173], v[156:157]
	v_pk_fma_f32 v[94:95], v[94:95], v[174:175], v[158:159]
	v_pk_fma_f32 v[96:97], v[96:97], v[176:177], v[160:161]
	v_pk_fma_f32 v[98:99], v[98:99], v[178:179], v[162:163]
	v_cvt_pk_bf16_f32 v240, v84, v85
	v_cvt_pk_bf16_f32 v241, v86, v87
	v_cvt_pk_bf16_f32 v242, v88, v89
	v_cvt_pk_bf16_f32 v243, v90, v91
	v_cvt_pk_bf16_f32 v244, v92, v93
	v_cvt_pk_bf16_f32 v245, v94, v95
	v_cvt_pk_bf16_f32 v246, v96, v97
	v_cvt_pk_bf16_f32 v247, v98, v99
	global_store_dwordx2 v1, v[240:241], s[10:11]
	global_store_dwordx2 v1, v[242:243], s[10:11] offset:512
	global_store_dwordx2 v1, v[244:245], s[10:11] offset:1024
	global_store_dwordx2 v1, v[246:247], s[10:11] offset:1536
	s_add_u32 s10, s10, 0x400000
	s_addc_u32 s11, s11, 0
	s_waitcnt vmcnt(24)
	v_pk_mul_f32 v[4:5], v[100:101], v[100:101]
	v_pk_fma_f32 v[4:5], v[102:103], v[102:103], v[4:5]
	v_pk_fma_f32 v[4:5], v[104:105], v[104:105], v[4:5]
	v_pk_fma_f32 v[4:5], v[106:107], v[106:107], v[4:5]
	v_pk_fma_f32 v[4:5], v[108:109], v[108:109], v[4:5]
	v_pk_fma_f32 v[4:5], v[110:111], v[110:111], v[4:5]
	v_pk_fma_f32 v[4:5], v[112:113], v[112:113], v[4:5]
	v_pk_fma_f32 v[4:5], v[114:115], v[114:115], v[4:5]
	v_add_f32_e32 v4, v4, v5
	s_nop 1
	v_add_f32_dpp v4, v4, v4 quad_perm:[1,0,3,2] row_mask:0xf bank_mask:0xf
	s_nop 1
	v_add_f32_dpp v4, v4, v4 quad_perm:[2,3,0,1] row_mask:0xf bank_mask:0xf
	s_nop 1
	v_add_f32_dpp v4, v4, v4 row_half_mirror row_mask:0xf bank_mask:0xf
	s_nop 1
	v_add_f32_dpp v4, v4, v4 row_mirror row_mask:0xf bank_mask:0xf
	s_nop 1
	v_add_f32_dpp v4, v4, v4 row_bcast:15 row_mask:0xa bank_mask:0xf
	s_nop 1
	v_add_f32_dpp v4, v4, v4 row_bcast:31 row_mask:0xc bank_mask:0xf
	s_nop 1
	v_readlane_b32 s20, v4, 63
	s_nop 1
	v_fma_f32 v6, s20, v16, v17
	v_rsq_f32_e32 v6, v6
	s_nop 0
	v_pk_mul_f32 v[100:101], v[100:101], v[6:7] op_sel_hi:[1,0]
	v_pk_mul_f32 v[102:103], v[102:103], v[6:7] op_sel_hi:[1,0]
	v_pk_mul_f32 v[104:105], v[104:105], v[6:7] op_sel_hi:[1,0]
	v_pk_mul_f32 v[106:107], v[106:107], v[6:7] op_sel_hi:[1,0]
	v_pk_mul_f32 v[108:109], v[108:109], v[6:7] op_sel_hi:[1,0]
	v_pk_mul_f32 v[110:111], v[110:111], v[6:7] op_sel_hi:[1,0]
	v_pk_mul_f32 v[112:113], v[112:113], v[6:7] op_sel_hi:[1,0]
	v_pk_mul_f32 v[114:115], v[114:115], v[6:7] op_sel_hi:[1,0]
	v_pk_mul_f32 v[100:101], v[100:101], v[20:21]
	v_pk_mul_f32 v[102:103], v[102:103], v[22:23]
	v_pk_mul_f32 v[104:105], v[104:105], v[24:25]
	v_pk_mul_f32 v[106:107], v[106:107], v[26:27]
	v_pk_mul_f32 v[108:109], v[108:109], v[28:29]
	v_pk_mul_f32 v[110:111], v[110:111], v[30:31]
	v_pk_mul_f32 v[112:113], v[112:113], v[32:33]
	v_pk_mul_f32 v[114:115], v[114:115], v[34:35]
	v_pk_fma_f32 v[100:101], v[100:101], v[164:165], v[148:149]
	v_pk_fma_f32 v[102:103], v[102:103], v[166:167], v[150:151]
	v_pk_fma_f32 v[104:105], v[104:105], v[168:169], v[152:153]
	v_pk_fma_f32 v[106:107], v[106:107], v[170:171], v[154:155]
	v_pk_fma_f32 v[108:109], v[108:109], v[172:173], v[156:157]
	v_pk_fma_f32 v[110:111], v[110:111], v[174:175], v[158:159]
	v_pk_fma_f32 v[112:113], v[112:113], v[176:177], v[160:161]
	v_pk_fma_f32 v[114:115], v[114:115], v[178:179], v[162:163]
	v_cvt_pk_bf16_f32 v232, v100, v101
	v_cvt_pk_bf16_f32 v233, v102, v103
	v_cvt_pk_bf16_f32 v234, v104, v105
	v_cvt_pk_bf16_f32 v235, v106, v107
	v_cvt_pk_bf16_f32 v236, v108, v109
	v_cvt_pk_bf16_f32 v237, v110, v111
	v_cvt_pk_bf16_f32 v238, v112, v113
	v_cvt_pk_bf16_f32 v239, v114, v115
	global_store_dwordx2 v1, v[232:233], s[10:11]
	global_store_dwordx2 v1, v[234:235], s[10:11] offset:512
	global_store_dwordx2 v1, v[236:237], s[10:11] offset:1024
	global_store_dwordx2 v1, v[238:239], s[10:11] offset:1536
	s_add_u32 s10, s10, 0x400000
	s_addc_u32 s11, s11, 0
	s_waitcnt vmcnt(20)
	v_pk_mul_f32 v[4:5], v[116:117], v[116:117]
	v_pk_fma_f32 v[4:5], v[118:119], v[118:119], v[4:5]
	v_pk_fma_f32 v[4:5], v[120:121], v[120:121], v[4:5]
	v_pk_fma_f32 v[4:5], v[122:123], v[122:123], v[4:5]
	v_pk_fma_f32 v[4:5], v[124:125], v[124:125], v[4:5]
	v_pk_fma_f32 v[4:5], v[126:127], v[126:127], v[4:5]
	v_pk_fma_f32 v[4:5], v[128:129], v[128:129], v[4:5]
	v_pk_fma_f32 v[4:5], v[130:131], v[130:131], v[4:5]
	v_add_f32_e32 v4, v4, v5
	s_nop 1
	v_add_f32_dpp v4, v4, v4 quad_perm:[1,0,3,2] row_mask:0xf bank_mask:0xf
	s_nop 1
	v_add_f32_dpp v4, v4, v4 quad_perm:[2,3,0,1] row_mask:0xf bank_mask:0xf
	s_nop 1
	v_add_f32_dpp v4, v4, v4 row_half_mirror row_mask:0xf bank_mask:0xf
	s_nop 1
	v_add_f32_dpp v4, v4, v4 row_mirror row_mask:0xf bank_mask:0xf
	s_nop 1
	v_add_f32_dpp v4, v4, v4 row_bcast:15 row_mask:0xa bank_mask:0xf
	s_nop 1
	v_add_f32_dpp v4, v4, v4 row_bcast:31 row_mask:0xc bank_mask:0xf
	s_nop 1
	v_readlane_b32 s20, v4, 63
	s_nop 1
	v_fma_f32 v6, s20, v16, v17
	v_rsq_f32_e32 v6, v6
	s_nop 0
	v_pk_mul_f32 v[116:117], v[116:117], v[6:7] op_sel_hi:[1,0]
	v_pk_mul_f32 v[118:119], v[118:119], v[6:7] op_sel_hi:[1,0]
	v_pk_mul_f32 v[120:121], v[120:121], v[6:7] op_sel_hi:[1,0]
	v_pk_mul_f32 v[122:123], v[122:123], v[6:7] op_sel_hi:[1,0]
	v_pk_mul_f32 v[124:125], v[124:125], v[6:7] op_sel_hi:[1,0]
	v_pk_mul_f32 v[126:127], v[126:127], v[6:7] op_sel_hi:[1,0]
	v_pk_mul_f32 v[128:129], v[128:129], v[6:7] op_sel_hi:[1,0]
	v_pk_mul_f32 v[130:131], v[130:131], v[6:7] op_sel_hi:[1,0]
	v_pk_mul_f32 v[116:117], v[116:117], v[20:21]
	v_pk_mul_f32 v[118:119], v[118:119], v[22:23]
	v_pk_mul_f32 v[120:121], v[120:121], v[24:25]
	v_pk_mul_f32 v[122:123], v[122:123], v[26:27]
	v_pk_mul_f32 v[124:125], v[124:125], v[28:29]
	v_pk_mul_f32 v[126:127], v[126:127], v[30:31]
	v_pk_mul_f32 v[128:129], v[128:129], v[32:33]
	v_pk_mul_f32 v[130:131], v[130:131], v[34:35]
	v_pk_fma_f32 v[116:117], v[116:117], v[164:165], v[148:149]
	v_pk_fma_f32 v[118:119], v[118:119], v[166:167], v[150:151]
	v_pk_fma_f32 v[120:121], v[120:121], v[168:169], v[152:153]
	v_pk_fma_f32 v[122:123], v[122:123], v[170:171], v[154:155]
	v_pk_fma_f32 v[124:125], v[124:125], v[172:173], v[156:157]
	v_pk_fma_f32 v[126:127], v[126:127], v[174:175], v[158:159]
	v_pk_fma_f32 v[128:129], v[128:129], v[176:177], v[160:161]
	v_pk_fma_f32 v[130:131], v[130:131], v[178:179], v[162:163]
	v_cvt_pk_bf16_f32 v240, v116, v117
	v_cvt_pk_bf16_f32 v241, v118, v119
	v_cvt_pk_bf16_f32 v242, v120, v121
	v_cvt_pk_bf16_f32 v243, v122, v123
	v_cvt_pk_bf16_f32 v244, v124, v125
	v_cvt_pk_bf16_f32 v245, v126, v127
	v_cvt_pk_bf16_f32 v246, v128, v129
	v_cvt_pk_bf16_f32 v247, v130, v131
	global_store_dwordx2 v1, v[240:241], s[10:11]
	global_store_dwordx2 v1, v[242:243], s[10:11] offset:512
	global_store_dwordx2 v1, v[244:245], s[10:11] offset:1024
	global_store_dwordx2 v1, v[246:247], s[10:11] offset:1536
	s_add_u32 s10, s10, 0x400000
	s_addc_u32 s11, s11, 0
	s_cmpk_lt_u32 s6, 0x400
	s_cbranch_scc0 .Lp1_done
	s_waitcnt vmcnt(16)
	v_pk_add_f32 v[52:53], v[52:53], v[18:19]
	v_pk_add_f32 v[54:55], v[54:55], v[18:19]
	v_pk_add_f32 v[56:57], v[56:57], v[18:19]
	v_pk_add_f32 v[58:59], v[58:59], v[18:19]
	v_pk_add_f32 v[60:61], v[60:61], v[18:19]
	v_pk_add_f32 v[62:63], v[62:63], v[18:19]
	v_pk_add_f32 v[64:65], v[64:65], v[18:19]
	v_pk_add_f32 v[66:67], v[66:67], v[18:19]
	s_lshl_b32 s10, s6, 11
	s_add_u32 s10, s10, 0x5e85000
	s_addc_u32 s11, 0, 0
	s_add_u32 s10, s74, s10
	s_addc_u32 s11, s75, s11
	v_pk_mul_f32 v[4:5], v[132:133], v[132:133]
	v_pk_fma_f32 v[4:5], v[134:135], v[134:135], v[4:5]
	v_pk_fma_f32 v[4:5], v[136:137], v[136:137], v[4:5]
	v_pk_fma_f32 v[4:5], v[138:139], v[138:139], v[4:5]
	v_pk_fma_f32 v[4:5], v[140:141], v[140:141], v[4:5]
	v_pk_fma_f32 v[4:5], v[142:143], v[142:143], v[4:5]
	v_pk_fma_f32 v[4:5], v[144:145], v[144:145], v[4:5]
	v_pk_fma_f32 v[4:5], v[146:147], v[146:147], v[4:5]
	v_add_f32_e32 v4, v4, v5
	s_nop 1
	v_add_f32_dpp v4, v4, v4 quad_perm:[1,0,3,2] row_mask:0xf bank_mask:0xf
	s_nop 1
	v_add_f32_dpp v4, v4, v4 quad_perm:[2,3,0,1] row_mask:0xf bank_mask:0xf
	s_nop 1
	v_add_f32_dpp v4, v4, v4 row_half_mirror row_mask:0xf bank_mask:0xf
	s_nop 1
	v_add_f32_dpp v4, v4, v4 row_mirror row_mask:0xf bank_mask:0xf
	s_nop 1
	v_add_f32_dpp v4, v4, v4 row_bcast:15 row_mask:0xa bank_mask:0xf
	s_nop 1
	v_add_f32_dpp v4, v4, v4 row_bcast:31 row_mask:0xc bank_mask:0xf
	s_nop 1
	v_readlane_b32 s20, v4, 63
	s_nop 1
	v_fma_f32 v6, s20, v16, v17
	v_rsq_f32_e32 v6, v6
	s_nop 0
	v_pk_mul_f32 v[132:133], v[132:133], v[6:7] op_sel_hi:[1,0]
	v_pk_mul_f32 v[134:135], v[134:135], v[6:7] op_sel_hi:[1,0]
	v_pk_mul_f32 v[136:137], v[136:137], v[6:7] op_sel_hi:[1,0]
	v_pk_mul_f32 v[138:139], v[138:139], v[6:7] op_sel_hi:[1,0]
	v_pk_mul_f32 v[140:141], v[140:141], v[6:7] op_sel_hi:[1,0]
	v_pk_mul_f32 v[142:143], v[142:143], v[6:7] op_sel_hi:[1,0]
	v_pk_mul_f32 v[144:145], v[144:145], v[6:7] op_sel_hi:[1,0]
	v_pk_mul_f32 v[146:147], v[146:147], v[6:7] op_sel_hi:[1,0]
	v_pk_mul_f32 v[132:133], v[132:133], v[20:21]
	v_pk_mul_f32 v[134:135], v[134:135], v[22:23]
	v_pk_mul_f32 v[136:137], v[136:137], v[24:25]
	v_pk_mul_f32 v[138:139], v[138:139], v[26:27]
	v_pk_mul_f32 v[140:141], v[140:141], v[28:29]
	v_pk_mul_f32 v[142:143], v[142:143], v[30:31]
	v_pk_mul_f32 v[144:145], v[144:145], v[32:33]
	v_pk_mul_f32 v[146:147], v[146:147], v[34:35]
	v_pk_fma_f32 v[132:133], v[132:133], v[52:53], v[36:37]
	v_pk_fma_f32 v[134:135], v[134:135], v[54:55], v[38:39]
	v_pk_fma_f32 v[136:137], v[136:137], v[56:57], v[40:41]
	v_pk_fma_f32 v[138:139], v[138:139], v[58:59], v[42:43]
	v_pk_fma_f32 v[140:141], v[140:141], v[60:61], v[44:45]
	v_pk_fma_f32 v[142:143], v[142:143], v[62:63], v[46:47]
	v_pk_fma_f32 v[144:145], v[144:145], v[64:65], v[48:49]
	v_pk_fma_f32 v[146:147], v[146:147], v[66:67], v[50:51]
	v_cvt_pk_bf16_f32 v232, v132, v133
	v_cvt_pk_bf16_f32 v233, v134, v135
	v_cvt_pk_bf16_f32 v234, v136, v137
	v_cvt_pk_bf16_f32 v235, v138, v139
	v_cvt_pk_bf16_f32 v236, v140, v141
	v_cvt_pk_bf16_f32 v237, v142, v143
	v_cvt_pk_bf16_f32 v238, v144, v145
	v_cvt_pk_bf16_f32 v239, v146, v147
	global_store_dwordx2 v1, v[232:233], s[10:11]
	global_store_dwordx2 v1, v[234:235], s[10:11] offset:512
	global_store_dwordx2 v1, v[236:237], s[10:11] offset:1024
	global_store_dwordx2 v1, v[238:239], s[10:11] offset:1536
.Lp1_done:
.LBB0_145:
	s_cmp_gt_i32 s77, 2
	s_cselect_b64 s[2:3], -1, 0
	s_and_b64 s[0:1], s[4:5], s[2:3]
	s_andn2_b64 vcc, exec, s[0:1]
	s_cbranch_vccnz .LBB0_199
	s_waitcnt vmcnt(0)
	s_barrier
	s_mov_b64 s[4:5], exec
	v_readlane_b32 s0, v250, 1
	v_readlane_b32 s1, v250, 2
	s_and_b64 s[0:1], s[4:5], s[0:1]
	s_mov_b64 exec, s[0:1]
	s_cbranch_execz .LBB0_198
	s_add_i32 s0, 0, 0x20000
	v_mov_b32_e32 v0, s0
	s_waitcnt vmcnt(0) expcnt(0) lgkmcnt(0)
	ds_read_b32 v2, v0
	s_add_i32 s0, 0, 0x20004
	v_mov_b32_e32 v0, s0
	ds_read_b32 v0, v0
	s_waitcnt lgkmcnt(1)
	v_cmp_ne_u32_e32 vcc, 0, v2
	s_cbranch_vccnz .LBB0_162
	s_add_u32 s6, s74, 0x1200
	s_addc_u32 s7, s75, 0
	s_add_u32 s8, s74, 0x1400
	s_addc_u32 s9, s75, 0
	s_add_u32 s10, s74, 0x1500
	s_addc_u32 s11, s75, 0
	s_add_u32 s12, s74, 0x1600
	s_addc_u32 s13, s75, 0
	s_add_u32 s14, s74, 0x1700
	s_addc_u32 s15, s75, 0
	s_add_u32 s16, s74, 0x1800
	s_addc_u32 s17, s75, 0
	s_add_u32 s18, s74, 0x1900
	s_addc_u32 s19, s75, 0
	s_add_u32 s20, s74, 0x1a00
	s_addc_u32 s21, s75, 0
	s_add_u32 s22, s74, 0x1b00
	s_addc_u32 s23, s75, 0
	s_add_u32 s24, s74, 0x1c00
	s_addc_u32 s25, s75, 0
	s_add_u32 s26, s74, 0x1d00
	s_addc_u32 s27, s75, 0
	s_add_u32 s28, s74, 0x1e00
	s_addc_u32 s29, s75, 0
	s_add_u32 s30, s74, 0x1f00
	s_addc_u32 s31, s75, 0
	s_add_u32 s34, s74, 0x2000
	s_addc_u32 s35, s75, 0
	s_add_u32 s36, s74, 0x2100
	s_addc_u32 s37, s75, 0
	s_add_u32 s42, s74, 0x2200
	v_readlane_b32 s0, v250, 0
	s_addc_u32 s43, s75, 0
	s_mul_i32 s0, s79, s0
	s_add_u32 s44, s74, 0x2300
	s_mul_i32 s0, s0, s78
	s_addc_u32 s45, s75, 0
	s_mov_b32 s1, 1
	v_mov_b32_e32 v16, 0
	s_branch .LBB0_150
